# write-through (sc0 sc1) stores for the GEMM epilogues of P1, P5, P8, P9 so the barrier-time buffer_wbl2 has little left to flush
# baseline (speedup 1.0000x reference)
.LBB0_277:
	v_lshl_add_u32 v144, s22, 8, v152
	v_ashrrev_i32_e32 v145, 31, v144
	v_lshl_add_u64 v[148:149], v[144:145], 2, s[6:7]
	global_load_dword v160, v[148:149], off
	v_lshl_or_b32 v150, s51, 8, v154
	v_mov_b64_e32 v[146:147], s[4:5]
	v_ashrrev_i32_e32 v151, 31, v150
	v_mad_i64_i32 v[162:163], s[24:25], v144, s50, v[146:147]
	v_or_b32_e32 v164, 16, v144
	v_lshlrev_b64 v[150:151], 1, v[150:151]
	v_ashrrev_i32_e32 v165, 31, v164
	v_lshl_add_u64 v[162:163], v[162:163], 0, v[150:151]
	v_lshl_add_u64 v[166:167], v[164:165], 2, s[6:7]
	s_andn2_b64 vcc, exec, s[0:1]
	s_mov_b64 s[0:1], -1
	s_waitcnt vmcnt(0)
	v_pk_mul_f32 v[126:127], v[126:127], v[160:161] op_sel_hi:[1,0]
	v_pk_mul_f32 v[124:125], v[124:125], v[160:161] op_sel_hi:[1,0]
	v_pk_mul_f32 v[122:123], v[122:123], v[160:161] op_sel_hi:[1,0]
	v_pk_mul_f32 v[120:121], v[120:121], v[160:161] op_sel_hi:[1,0]
	v_pk_mul_f32 v[118:119], v[118:119], v[160:161] op_sel_hi:[1,0]
	v_pk_mul_f32 v[116:117], v[116:117], v[160:161] op_sel_hi:[1,0]
	v_pk_mul_f32 v[168:169], v[114:115], v[160:161] op_sel_hi:[1,0]
	v_pk_mul_f32 v[160:161], v[112:113], v[160:161] op_sel_hi:[1,0]
	v_cvt_pk_bf16_f32 v112, v124, v125
	v_cvt_pk_bf16_f32 v113, v126, v127
	v_cvt_pk_bf16_f32 v114, v120, v121
	v_cvt_pk_bf16_f32 v115, v122, v123
	global_store_dwordx4 v[162:163], v[112:115], off sc0 sc1
	s_nop 1
	v_cvt_pk_bf16_f32 v112, v116, v117
	v_cvt_pk_bf16_f32 v113, v118, v119
	v_cvt_pk_bf16_f32 v114, v160, v161
	v_cvt_pk_bf16_f32 v115, v168, v169
	global_store_dwordx4 v[162:163], v[112:115], off offset:256 sc0 sc1
	global_load_dword v112, v[166:167], off
	v_mad_i64_i32 v[116:117], s[24:25], v164, s50, v[146:147]
	v_or_b32_e32 v114, 32, v144
	v_ashrrev_i32_e32 v115, 31, v114
	v_lshl_add_u64 v[116:117], v[116:117], 0, v[150:151]
	v_lshl_add_u64 v[118:119], v[114:115], 2, s[6:7]
	s_waitcnt vmcnt(0)
	v_pk_mul_f32 v[110:111], v[110:111], v[112:113] op_sel_hi:[1,0]
	v_pk_mul_f32 v[108:109], v[108:109], v[112:113] op_sel_hi:[1,0]
	v_pk_mul_f32 v[106:107], v[106:107], v[112:113] op_sel_hi:[1,0]
	v_pk_mul_f32 v[104:105], v[104:105], v[112:113] op_sel_hi:[1,0]
	v_pk_mul_f32 v[102:103], v[102:103], v[112:113] op_sel_hi:[1,0]
	v_pk_mul_f32 v[100:101], v[100:101], v[112:113] op_sel_hi:[1,0]
	v_pk_mul_f32 v[120:121], v[98:99], v[112:113] op_sel_hi:[1,0]
	v_pk_mul_f32 v[112:113], v[96:97], v[112:113] op_sel_hi:[1,0]
	v_cvt_pk_bf16_f32 v96, v108, v109
	v_cvt_pk_bf16_f32 v97, v110, v111
	v_cvt_pk_bf16_f32 v98, v104, v105
	v_cvt_pk_bf16_f32 v99, v106, v107
	global_store_dwordx4 v[116:117], v[96:99], off sc0 sc1
	s_nop 1
	v_cvt_pk_bf16_f32 v96, v100, v101
	v_cvt_pk_bf16_f32 v97, v102, v103
	v_cvt_pk_bf16_f32 v98, v112, v113
	v_cvt_pk_bf16_f32 v99, v120, v121
	global_store_dwordx4 v[116:117], v[96:99], off offset:256 sc0 sc1
	global_load_dword v96, v[118:119], off
	v_mad_i64_i32 v[100:101], s[24:25], v114, s50, v[146:147]
	v_or_b32_e32 v98, 48, v144
	v_ashrrev_i32_e32 v99, 31, v98
	v_lshl_add_u64 v[100:101], v[100:101], 0, v[150:151]
	v_lshl_add_u64 v[102:103], v[98:99], 2, s[6:7]
	s_waitcnt vmcnt(0)
	v_pk_mul_f32 v[94:95], v[94:95], v[96:97] op_sel_hi:[1,0]
	v_pk_mul_f32 v[92:93], v[92:93], v[96:97] op_sel_hi:[1,0]
	v_pk_mul_f32 v[90:91], v[90:91], v[96:97] op_sel_hi:[1,0]
	v_pk_mul_f32 v[88:89], v[88:89], v[96:97] op_sel_hi:[1,0]
	v_pk_mul_f32 v[82:83], v[82:83], v[96:97] op_sel_hi:[1,0]
	v_pk_mul_f32 v[80:81], v[80:81], v[96:97] op_sel_hi:[1,0]
	v_pk_mul_f32 v[104:105], v[74:75], v[96:97] op_sel_hi:[1,0]
	v_pk_mul_f32 v[96:97], v[72:73], v[96:97] op_sel_hi:[1,0]
	v_cvt_pk_bf16_f32 v72, v92, v93
	v_cvt_pk_bf16_f32 v73, v94, v95
	v_cvt_pk_bf16_f32 v74, v88, v89
	v_cvt_pk_bf16_f32 v75, v90, v91
	global_store_dwordx4 v[100:101], v[72:75], off sc0 sc1
	s_nop 1
	v_cvt_pk_bf16_f32 v72, v80, v81
	v_cvt_pk_bf16_f32 v73, v82, v83
	v_cvt_pk_bf16_f32 v74, v96, v97
	v_cvt_pk_bf16_f32 v75, v104, v105
	global_store_dwordx4 v[100:101], v[72:75], off offset:256 sc0 sc1
	global_load_dword v72, v[102:103], off
	s_waitcnt vmcnt(0)
	v_pk_mul_f32 v[80:81], v[86:87], v[72:73] op_sel_hi:[1,0]
	v_mad_i64_i32 v[74:75], s[24:25], v98, s50, v[146:147]
	v_lshl_add_u64 v[74:75], v[74:75], 0, v[150:151]
	v_pk_mul_f32 v[82:83], v[84:85], v[72:73] op_sel_hi:[1,0]
	v_pk_mul_f32 v[78:79], v[78:79], v[72:73] op_sel_hi:[1,0]
	v_pk_mul_f32 v[76:77], v[76:77], v[72:73] op_sel_hi:[1,0]
	v_pk_mul_f32 v[70:71], v[70:71], v[72:73] op_sel_hi:[1,0]
	v_pk_mul_f32 v[68:69], v[68:69], v[72:73] op_sel_hi:[1,0]
	v_pk_mul_f32 v[84:85], v[66:67], v[72:73] op_sel_hi:[1,0]
	v_pk_mul_f32 v[72:73], v[64:65], v[72:73] op_sel_hi:[1,0]
	v_cvt_pk_bf16_f32 v64, v82, v83
	v_cvt_pk_bf16_f32 v65, v80, v81
	v_cvt_pk_bf16_f32 v66, v76, v77
	v_cvt_pk_bf16_f32 v67, v78, v79
	global_store_dwordx4 v[74:75], v[64:67], off sc0 sc1
	s_nop 1
	v_cvt_pk_bf16_f32 v64, v68, v69
	v_cvt_pk_bf16_f32 v65, v70, v71
	v_cvt_pk_bf16_f32 v66, v72, v73
	v_cvt_pk_bf16_f32 v67, v84, v85
	global_store_dwordx4 v[74:75], v[64:67], off offset:256 sc0 sc1
	global_load_dword v64, v[148:149], off offset:512
	s_nop 0
	v_add_u32_e32 v65, 0x80, v144
	v_mad_i64_i32 v[66:67], s[24:25], v65, s50, v[146:147]
	v_lshl_add_u64 v[66:67], v[66:67], 0, v[150:151]
	s_waitcnt vmcnt(0)
	v_pk_mul_f32 v[62:63], v[62:63], v[64:65] op_sel_hi:[1,0]
	v_pk_mul_f32 v[60:61], v[60:61], v[64:65] op_sel_hi:[1,0]
	v_pk_mul_f32 v[58:59], v[58:59], v[64:65] op_sel_hi:[1,0]
	v_pk_mul_f32 v[56:57], v[56:57], v[64:65] op_sel_hi:[1,0]
	v_pk_mul_f32 v[54:55], v[54:55], v[64:65] op_sel_hi:[1,0]
	v_pk_mul_f32 v[52:53], v[52:53], v[64:65] op_sel_hi:[1,0]
	v_pk_mul_f32 v[68:69], v[50:51], v[64:65] op_sel_hi:[1,0]
	v_pk_mul_f32 v[64:65], v[48:49], v[64:65] op_sel_hi:[1,0]
	v_cvt_pk_bf16_f32 v48, v60, v61
	v_cvt_pk_bf16_f32 v49, v62, v63
	v_cvt_pk_bf16_f32 v50, v56, v57
	v_cvt_pk_bf16_f32 v51, v58, v59
	global_store_dwordx4 v[66:67], v[48:51], off sc0 sc1
	s_nop 1
	v_cvt_pk_bf16_f32 v48, v52, v53
	v_cvt_pk_bf16_f32 v49, v54, v55
	v_cvt_pk_bf16_f32 v50, v64, v65
	v_cvt_pk_bf16_f32 v51, v68, v69
	global_store_dwordx4 v[66:67], v[48:51], off offset:256 sc0 sc1
	global_load_dword v48, v[148:149], off offset:576
	s_nop 0
	v_add_u32_e32 v49, 0x90, v144
	v_mad_i64_i32 v[50:51], s[24:25], v49, s50, v[146:147]
	v_lshl_add_u64 v[50:51], v[50:51], 0, v[150:151]
	s_waitcnt vmcnt(0)
	v_pk_mul_f32 v[46:47], v[46:47], v[48:49] op_sel_hi:[1,0]
	v_pk_mul_f32 v[44:45], v[44:45], v[48:49] op_sel_hi:[1,0]
	v_pk_mul_f32 v[42:43], v[42:43], v[48:49] op_sel_hi:[1,0]
	v_pk_mul_f32 v[40:41], v[40:41], v[48:49] op_sel_hi:[1,0]
	v_pk_mul_f32 v[38:39], v[38:39], v[48:49] op_sel_hi:[1,0]
	v_pk_mul_f32 v[36:37], v[36:37], v[48:49] op_sel_hi:[1,0]
	v_pk_mul_f32 v[52:53], v[34:35], v[48:49] op_sel_hi:[1,0]
	v_pk_mul_f32 v[48:49], v[32:33], v[48:49] op_sel_hi:[1,0]
	v_cvt_pk_bf16_f32 v32, v44, v45
	v_cvt_pk_bf16_f32 v33, v46, v47
	v_cvt_pk_bf16_f32 v34, v40, v41
	v_cvt_pk_bf16_f32 v35, v42, v43
	global_store_dwordx4 v[50:51], v[32:35], off sc0 sc1
	s_nop 1
	v_cvt_pk_bf16_f32 v32, v36, v37
	v_cvt_pk_bf16_f32 v33, v38, v39
	v_cvt_pk_bf16_f32 v34, v48, v49
	v_cvt_pk_bf16_f32 v35, v52, v53
	global_store_dwordx4 v[50:51], v[32:35], off offset:256 sc0 sc1
	global_load_dword v32, v[148:149], off offset:640
	s_nop 0
	v_add_u32_e32 v33, 0xa0, v144
	v_mad_i64_i32 v[34:35], s[24:25], v33, s50, v[146:147]
	v_lshl_add_u64 v[34:35], v[34:35], 0, v[150:151]
	s_waitcnt vmcnt(0)
	v_pk_mul_f32 v[30:31], v[30:31], v[32:33] op_sel_hi:[1,0]
	v_pk_mul_f32 v[28:29], v[28:29], v[32:33] op_sel_hi:[1,0]
	v_pk_mul_f32 v[26:27], v[26:27], v[32:33] op_sel_hi:[1,0]
	v_pk_mul_f32 v[24:25], v[24:25], v[32:33] op_sel_hi:[1,0]
	v_pk_mul_f32 v[22:23], v[22:23], v[32:33] op_sel_hi:[1,0]
	v_pk_mul_f32 v[20:21], v[20:21], v[32:33] op_sel_hi:[1,0]
	v_pk_mul_f32 v[36:37], v[18:19], v[32:33] op_sel_hi:[1,0]
	v_pk_mul_f32 v[32:33], v[16:17], v[32:33] op_sel_hi:[1,0]
	v_cvt_pk_bf16_f32 v16, v28, v29
	v_cvt_pk_bf16_f32 v17, v30, v31
	v_cvt_pk_bf16_f32 v18, v24, v25
	v_cvt_pk_bf16_f32 v19, v26, v27
	global_store_dwordx4 v[34:35], v[16:19], off sc0 sc1
	s_nop 1
	v_cvt_pk_bf16_f32 v16, v20, v21
	v_cvt_pk_bf16_f32 v17, v22, v23
	v_cvt_pk_bf16_f32 v18, v32, v33
	v_cvt_pk_bf16_f32 v19, v36, v37
	global_store_dwordx4 v[34:35], v[16:19], off offset:256 sc0 sc1
	global_load_dword v16, v[148:149], off offset:704
	s_nop 0
	v_add_u32_e32 v17, 0xb0, v144
	v_mad_i64_i32 v[18:19], s[24:25], v17, s50, v[146:147]
	v_lshl_add_u64 v[18:19], v[18:19], 0, v[150:151]
	s_waitcnt vmcnt(0)
	v_pk_mul_f32 v[14:15], v[14:15], v[16:17] op_sel_hi:[1,0]
	v_pk_mul_f32 v[12:13], v[12:13], v[16:17] op_sel_hi:[1,0]
	v_pk_mul_f32 v[10:11], v[10:11], v[16:17] op_sel_hi:[1,0]
	v_pk_mul_f32 v[8:9], v[8:9], v[16:17] op_sel_hi:[1,0]
	v_pk_mul_f32 v[6:7], v[6:7], v[16:17] op_sel_hi:[1,0]
	v_pk_mul_f32 v[4:5], v[4:5], v[16:17] op_sel_hi:[1,0]
	v_pk_mul_f32 v[20:21], v[2:3], v[16:17] op_sel_hi:[1,0]
	v_pk_mul_f32 v[16:17], v[0:1], v[16:17] op_sel_hi:[1,0]
	v_cvt_pk_bf16_f32 v0, v12, v13
	v_cvt_pk_bf16_f32 v1, v14, v15
	v_cvt_pk_bf16_f32 v2, v8, v9
	v_cvt_pk_bf16_f32 v3, v10, v11
	global_store_dwordx4 v[18:19], v[0:3], off sc0 sc1
	s_nop 1
	v_cvt_pk_bf16_f32 v0, v4, v5
	v_cvt_pk_bf16_f32 v1, v6, v7
	v_cvt_pk_bf16_f32 v2, v16, v17
	v_cvt_pk_bf16_f32 v3, v20, v21
	global_store_dwordx4 v[18:19], v[0:3], off offset:256 sc0 sc1
	s_cbranch_vccnz .LBB0_270
	s_andn2_b64 vcc, exec, s[2:3]
	s_cbranch_vccnz .LBB0_269
	s_barrier
	s_branch .LBB0_269

.Lmy_wup_begin:
	s_cmpk_lg_u32 s88, 0x100
	s_cbranch_scc1 .Lmy_wup_end
	s_waitcnt lgkmcnt(0)
	s_barrier
	v_readlane_b32 s2, v252, 0
	v_readlane_b32 s3, v252, 1
	s_add_u32 s2, s2, 0xffffff20
	s_addc_u32 s3, s3, -1
	s_load_dwordx4 s[4:7], s[2:3], 0xb0
	v_and_b32_e32 v197, 63, v158
	v_lshrrev_b32_e32 v198, 4, v197
	v_and_b32_e32 v194, 15, v197
	v_lshlrev_b32_e32 v194, 2, v194
	v_mul_u32_u24_e32 v193, 0x4100, v159
	v_mul_u32_u24_e32 v192, 65, v198
	v_add_u32_e32 v192, v192, v194
	v_lshl_add_u32 v176, v192, 2, v193
	v_add_u32_e32 v177, 0x410, v176
	v_add_u32_e32 v178, 0x820, v176
	v_add_u32_e32 v179, 0xc30, v176
	v_add_u32_e32 v180, 0x1040, v176
	v_add_u32_e32 v181, 0x1450, v176
	v_add_u32_e32 v182, 0x1860, v176
	v_add_u32_e32 v183, 0x1c70, v176
	v_add_u32_e32 v184, 0x2080, v176
	v_add_u32_e32 v185, 0x2490, v176
	v_add_u32_e32 v186, 0x28a0, v176
	v_add_u32_e32 v187, 0x2cb0, v176
	v_add_u32_e32 v188, 0x30c0, v176
	v_add_u32_e32 v189, 0x34d0, v176
	v_add_u32_e32 v190, 0x38e0, v176
	v_add_u32_e32 v191, 0x3cf0, v176
	v_lshlrev_b32_e32 v195, 2, v198
	v_lshlrev_b32_e32 v194, 2, v194
	v_lshl_add_u32 v194, v198, 15, v194
	v_and_b32_e32 v196, 7, v197
	v_mul_u32_u24_e32 v192, 0x208, v196
	v_lshrrev_b32_e32 v198, 3, v197
	v_add_u32_e32 v192, v192, v198
	v_lshl_add_u32 v192, v192, 2, v193
	v_add_u32_e32 v193, 0x400, v192
	v_lshlrev_b32_e32 v196, 4, v196
	v_lshl_add_u32 v196, v198, 12, v196
	v_readfirstlane_b32 s8, v159
	s_lshl_b32 s9, s33, 3
	s_add_i32 s8, s8, s9
	s_waitcnt lgkmcnt(0)
	s_lshr_b32 s9, s8, 7
	s_and_b32 s10, s8, 0x7f
	s_lshl_b32 s11, s9, 21
	s_lshl_b32 s12, s10, 8
	s_add_u32 s11, s11, s12
	s_add_u32 s16, s6, s11
	s_addc_u32 s17, s7, 0
	s_lshl_b32 s11, s9, 8
	s_add_u32 s18, s4, s11
	s_addc_u32 s19, s5, 0
	s_lshl_b32 s11, s10, 18
	s_lshl_b32 s12, s9, 7
	s_add_u32 s11, s11, s12
	s_add_u32 s11, s11, 0x1000000
	s_add_u32 s20, s84, s11
	s_addc_u32 s21, s85, 0
	s_addk_i32 s8, 0x800
	s_lshr_b32 s9, s8, 7
	s_and_b32 s10, s8, 0x7f
	s_lshl_b32 s11, s9, 21
	s_lshl_b32 s12, s10, 8
	s_add_u32 s11, s11, s12
	s_add_u32 s22, s6, s11
	s_addc_u32 s23, s7, 0
	s_lshl_b32 s11, s9, 8
	s_add_u32 s24, s4, s11
	s_addc_u32 s25, s5, 0
	s_lshl_b32 s11, s10, 18
	s_lshl_b32 s12, s9, 7
	s_add_u32 s11, s11, s12
	s_add_u32 s11, s11, 0x1000000
	s_add_u32 s26, s84, s11
	s_addc_u32 s27, s85, 0
	global_load_dword v128, v195, s[18:19]
	global_load_dword v129, v195, s[18:19] offset:16
	global_load_dword v130, v195, s[18:19] offset:32
	global_load_dword v131, v195, s[18:19] offset:48
	global_load_dword v132, v195, s[18:19] offset:64
	global_load_dword v133, v195, s[18:19] offset:80
	global_load_dword v134, v195, s[18:19] offset:96
	global_load_dword v135, v195, s[18:19] offset:112
	global_load_dword v136, v195, s[18:19] offset:128
	global_load_dword v137, v195, s[18:19] offset:144
	global_load_dword v138, v195, s[18:19] offset:160
	global_load_dword v139, v195, s[18:19] offset:176
	global_load_dword v140, v195, s[18:19] offset:192
	global_load_dword v141, v195, s[18:19] offset:208
	global_load_dword v142, v195, s[18:19] offset:224
	global_load_dword v143, v195, s[18:19] offset:240
	v_mov_b32_e32 v197, v194
	global_load_dwordx4 v[0:3], v197, s[16:17] nt
	v_add_u32_e32 v197, 0x20000, v197
	global_load_dwordx4 v[4:7], v197, s[16:17] nt
	v_add_u32_e32 v197, 0x20000, v197
	global_load_dwordx4 v[8:11], v197, s[16:17] nt
	v_add_u32_e32 v197, 0x20000, v197
	global_load_dwordx4 v[12:15], v197, s[16:17] nt
	v_add_u32_e32 v197, 0x20000, v197
	global_load_dwordx4 v[16:19], v197, s[16:17] nt
	v_add_u32_e32 v197, 0x20000, v197
	global_load_dwordx4 v[20:23], v197, s[16:17] nt
	v_add_u32_e32 v197, 0x20000, v197
	global_load_dwordx4 v[24:27], v197, s[16:17] nt
	v_add_u32_e32 v197, 0x20000, v197
	global_load_dwordx4 v[28:31], v197, s[16:17] nt
	v_add_u32_e32 v197, 0x20000, v197
	global_load_dwordx4 v[32:35], v197, s[16:17] nt
	v_add_u32_e32 v197, 0x20000, v197
	global_load_dwordx4 v[36:39], v197, s[16:17] nt
	v_add_u32_e32 v197, 0x20000, v197
	global_load_dwordx4 v[40:43], v197, s[16:17] nt
	v_add_u32_e32 v197, 0x20000, v197
	global_load_dwordx4 v[44:47], v197, s[16:17] nt
	v_add_u32_e32 v197, 0x20000, v197
	global_load_dwordx4 v[48:51], v197, s[16:17] nt
	v_add_u32_e32 v197, 0x20000, v197
	global_load_dwordx4 v[52:55], v197, s[16:17] nt
	v_add_u32_e32 v197, 0x20000, v197
	global_load_dwordx4 v[56:59], v197, s[16:17] nt
	v_add_u32_e32 v197, 0x20000, v197
	global_load_dwordx4 v[60:63], v197, s[16:17] nt
	global_load_dword v160, v195, s[24:25]
	global_load_dword v161, v195, s[24:25] offset:16
	global_load_dword v162, v195, s[24:25] offset:32
	global_load_dword v163, v195, s[24:25] offset:48
	global_load_dword v164, v195, s[24:25] offset:64
	global_load_dword v165, v195, s[24:25] offset:80
	global_load_dword v166, v195, s[24:25] offset:96
	global_load_dword v167, v195, s[24:25] offset:112
	global_load_dword v168, v195, s[24:25] offset:128
	global_load_dword v169, v195, s[24:25] offset:144
	global_load_dword v170, v195, s[24:25] offset:160
	global_load_dword v171, v195, s[24:25] offset:176
	global_load_dword v172, v195, s[24:25] offset:192
	global_load_dword v173, v195, s[24:25] offset:208
	global_load_dword v174, v195, s[24:25] offset:224
	global_load_dword v175, v195, s[24:25] offset:240
	v_mov_b32_e32 v197, v194
	global_load_dwordx4 v[64:67], v197, s[22:23] nt
	v_add_u32_e32 v197, 0x20000, v197
	global_load_dwordx4 v[68:71], v197, s[22:23] nt
	v_add_u32_e32 v197, 0x20000, v197
	global_load_dwordx4 v[72:75], v197, s[22:23] nt
	v_add_u32_e32 v197, 0x20000, v197
	global_load_dwordx4 v[76:79], v197, s[22:23] nt
	v_add_u32_e32 v197, 0x20000, v197
	global_load_dwordx4 v[80:83], v197, s[22:23] nt
	v_add_u32_e32 v197, 0x20000, v197
	global_load_dwordx4 v[84:87], v197, s[22:23] nt
	v_add_u32_e32 v197, 0x20000, v197
	global_load_dwordx4 v[88:91], v197, s[22:23] nt
	v_add_u32_e32 v197, 0x20000, v197
	global_load_dwordx4 v[92:95], v197, s[22:23] nt
	v_add_u32_e32 v197, 0x20000, v197
	global_load_dwordx4 v[96:99], v197, s[22:23] nt
	v_add_u32_e32 v197, 0x20000, v197
	global_load_dwordx4 v[100:103], v197, s[22:23] nt
	v_add_u32_e32 v197, 0x20000, v197
	global_load_dwordx4 v[104:107], v197, s[22:23] nt
	v_add_u32_e32 v197, 0x20000, v197
	global_load_dwordx4 v[108:111], v197, s[22:23] nt
	v_add_u32_e32 v197, 0x20000, v197
	global_load_dwordx4 v[112:115], v197, s[22:23] nt
	v_add_u32_e32 v197, 0x20000, v197
	global_load_dwordx4 v[116:119], v197, s[22:23] nt
	v_add_u32_e32 v197, 0x20000, v197
	global_load_dwordx4 v[120:123], v197, s[22:23] nt
	v_add_u32_e32 v197, 0x20000, v197
	global_load_dwordx4 v[124:127], v197, s[22:23] nt
	s_waitcnt vmcnt(47)
	v_mul_f32_e32 v0, v0, v128
	v_mul_f32_e32 v1, v1, v128
	v_mul_f32_e32 v2, v2, v128
	v_mul_f32_e32 v3, v3, v128
	ds_write2_b32 v176, v0, v1 offset1:1
	ds_write2_b32 v176, v2, v3 offset0:2 offset1:3
	s_waitcnt vmcnt(46)
	v_mul_f32_e32 v4, v4, v129
	v_mul_f32_e32 v5, v5, v129
	v_mul_f32_e32 v6, v6, v129
	v_mul_f32_e32 v7, v7, v129
	ds_write2_b32 v177, v4, v5 offset1:1
	ds_write2_b32 v177, v6, v7 offset0:2 offset1:3
	s_waitcnt vmcnt(45)
	v_mul_f32_e32 v8, v8, v130
	v_mul_f32_e32 v9, v9, v130
	v_mul_f32_e32 v10, v10, v130
	v_mul_f32_e32 v11, v11, v130
	ds_write2_b32 v178, v8, v9 offset1:1
	ds_write2_b32 v178, v10, v11 offset0:2 offset1:3
	s_waitcnt vmcnt(44)
	v_mul_f32_e32 v12, v12, v131
	v_mul_f32_e32 v13, v13, v131
	v_mul_f32_e32 v14, v14, v131
	v_mul_f32_e32 v15, v15, v131
	ds_write2_b32 v179, v12, v13 offset1:1
	ds_write2_b32 v179, v14, v15 offset0:2 offset1:3
	s_waitcnt vmcnt(43)
	v_mul_f32_e32 v16, v16, v132
	v_mul_f32_e32 v17, v17, v132
	v_mul_f32_e32 v18, v18, v132
	v_mul_f32_e32 v19, v19, v132
	ds_write2_b32 v180, v16, v17 offset1:1
	ds_write2_b32 v180, v18, v19 offset0:2 offset1:3
	s_waitcnt vmcnt(42)
	v_mul_f32_e32 v20, v20, v133
	v_mul_f32_e32 v21, v21, v133
	v_mul_f32_e32 v22, v22, v133
	v_mul_f32_e32 v23, v23, v133
	ds_write2_b32 v181, v20, v21 offset1:1
	ds_write2_b32 v181, v22, v23 offset0:2 offset1:3
	s_waitcnt vmcnt(41)
	v_mul_f32_e32 v24, v24, v134
	v_mul_f32_e32 v25, v25, v134
	v_mul_f32_e32 v26, v26, v134
	v_mul_f32_e32 v27, v27, v134
	ds_write2_b32 v182, v24, v25 offset1:1
	ds_write2_b32 v182, v26, v27 offset0:2 offset1:3
	s_waitcnt vmcnt(40)
	v_mul_f32_e32 v28, v28, v135
	v_mul_f32_e32 v29, v29, v135
	v_mul_f32_e32 v30, v30, v135
	v_mul_f32_e32 v31, v31, v135
	ds_write2_b32 v183, v28, v29 offset1:1
	ds_write2_b32 v183, v30, v31 offset0:2 offset1:3
	s_waitcnt vmcnt(39)
	v_mul_f32_e32 v32, v32, v136
	v_mul_f32_e32 v33, v33, v136
	v_mul_f32_e32 v34, v34, v136
	v_mul_f32_e32 v35, v35, v136
	ds_write2_b32 v184, v32, v33 offset1:1
	ds_write2_b32 v184, v34, v35 offset0:2 offset1:3
	s_waitcnt vmcnt(38)
	v_mul_f32_e32 v36, v36, v137
	v_mul_f32_e32 v37, v37, v137
	v_mul_f32_e32 v38, v38, v137
	v_mul_f32_e32 v39, v39, v137
	ds_write2_b32 v185, v36, v37 offset1:1
	ds_write2_b32 v185, v38, v39 offset0:2 offset1:3
	s_waitcnt vmcnt(37)
	v_mul_f32_e32 v40, v40, v138
	v_mul_f32_e32 v41, v41, v138
	v_mul_f32_e32 v42, v42, v138
	v_mul_f32_e32 v43, v43, v138
	ds_write2_b32 v186, v40, v41 offset1:1
	ds_write2_b32 v186, v42, v43 offset0:2 offset1:3
	s_waitcnt vmcnt(36)
	v_mul_f32_e32 v44, v44, v139
	v_mul_f32_e32 v45, v45, v139
	v_mul_f32_e32 v46, v46, v139
	v_mul_f32_e32 v47, v47, v139
	ds_write2_b32 v187, v44, v45 offset1:1
	ds_write2_b32 v187, v46, v47 offset0:2 offset1:3
	s_waitcnt vmcnt(35)
	v_mul_f32_e32 v48, v48, v140
	v_mul_f32_e32 v49, v49, v140
	v_mul_f32_e32 v50, v50, v140
	v_mul_f32_e32 v51, v51, v140
	ds_write2_b32 v188, v48, v49 offset1:1
	ds_write2_b32 v188, v50, v51 offset0:2 offset1:3
	s_waitcnt vmcnt(34)
	v_mul_f32_e32 v52, v52, v141
	v_mul_f32_e32 v53, v53, v141
	v_mul_f32_e32 v54, v54, v141
	v_mul_f32_e32 v55, v55, v141
	ds_write2_b32 v189, v52, v53 offset1:1
	ds_write2_b32 v189, v54, v55 offset0:2 offset1:3
	s_waitcnt vmcnt(33)
	v_mul_f32_e32 v56, v56, v142
	v_mul_f32_e32 v57, v57, v142
	v_mul_f32_e32 v58, v58, v142
	v_mul_f32_e32 v59, v59, v142
	ds_write2_b32 v190, v56, v57 offset1:1
	ds_write2_b32 v190, v58, v59 offset0:2 offset1:3
	s_waitcnt vmcnt(32)
	v_mul_f32_e32 v60, v60, v143
	v_mul_f32_e32 v61, v61, v143
	v_mul_f32_e32 v62, v62, v143
	v_mul_f32_e32 v63, v63, v143
	ds_write2_b32 v191, v60, v61 offset1:1
	ds_write2_b32 v191, v62, v63 offset0:2 offset1:3
	s_waitcnt lgkmcnt(0)
	v_mov_b32_e32 v197, v196
	ds_read2_b32 v[208:209], v192 offset0:0 offset1:65
	ds_read2_b32 v[210:211], v192 offset0:130 offset1:195
	ds_read2_b32 v[212:213], v193 offset0:4 offset1:69
	ds_read2_b32 v[214:215], v193 offset0:134 offset1:199
	ds_read2_b32 v[216:217], v192 offset0:8 offset1:73
	ds_read2_b32 v[218:219], v192 offset0:138 offset1:203
	ds_read2_b32 v[220:221], v193 offset0:12 offset1:77
	ds_read2_b32 v[222:223], v193 offset0:142 offset1:207
	s_waitcnt lgkmcnt(4)
	v_cvt_pk_bf16_f32 v200, v208, v209
	v_cvt_pk_bf16_f32 v201, v210, v211
	v_cvt_pk_bf16_f32 v202, v212, v213
	v_cvt_pk_bf16_f32 v203, v214, v215
	global_store_dwordx4 v197, v[200:203], s[20:21] sc0 sc1
	v_add_u32_e32 v197, 0x8000, v197
	s_waitcnt lgkmcnt(0)
	v_cvt_pk_bf16_f32 v204, v216, v217
	v_cvt_pk_bf16_f32 v205, v218, v219
	v_cvt_pk_bf16_f32 v206, v220, v221
	v_cvt_pk_bf16_f32 v207, v222, v223
	global_store_dwordx4 v197, v[204:207], s[20:21] sc0 sc1
	v_add_u32_e32 v197, 0x8000, v197
	ds_read2_b32 v[208:209], v192 offset0:16 offset1:81
	ds_read2_b32 v[210:211], v192 offset0:146 offset1:211
	ds_read2_b32 v[212:213], v193 offset0:20 offset1:85
	ds_read2_b32 v[214:215], v193 offset0:150 offset1:215
	ds_read2_b32 v[216:217], v192 offset0:24 offset1:89
	ds_read2_b32 v[218:219], v192 offset0:154 offset1:219
	ds_read2_b32 v[220:221], v193 offset0:28 offset1:93
	ds_read2_b32 v[222:223], v193 offset0:158 offset1:223
	s_waitcnt lgkmcnt(4)
	v_cvt_pk_bf16_f32 v200, v208, v209
	v_cvt_pk_bf16_f32 v201, v210, v211
	v_cvt_pk_bf16_f32 v202, v212, v213
	v_cvt_pk_bf16_f32 v203, v214, v215
	global_store_dwordx4 v197, v[200:203], s[20:21] sc0 sc1
	v_add_u32_e32 v197, 0x8000, v197
	s_waitcnt lgkmcnt(0)
	v_cvt_pk_bf16_f32 v204, v216, v217
	v_cvt_pk_bf16_f32 v205, v218, v219
	v_cvt_pk_bf16_f32 v206, v220, v221
	v_cvt_pk_bf16_f32 v207, v222, v223
	global_store_dwordx4 v197, v[204:207], s[20:21] sc0 sc1
	v_add_u32_e32 v197, 0x8000, v197
	ds_read2_b32 v[208:209], v192 offset0:32 offset1:97
	ds_read2_b32 v[210:211], v192 offset0:162 offset1:227
	ds_read2_b32 v[212:213], v193 offset0:36 offset1:101
	ds_read2_b32 v[214:215], v193 offset0:166 offset1:231
	ds_read2_b32 v[216:217], v192 offset0:40 offset1:105
	ds_read2_b32 v[218:219], v192 offset0:170 offset1:235
	ds_read2_b32 v[220:221], v193 offset0:44 offset1:109
	ds_read2_b32 v[222:223], v193 offset0:174 offset1:239
	s_waitcnt lgkmcnt(4)
	v_cvt_pk_bf16_f32 v200, v208, v209
	v_cvt_pk_bf16_f32 v201, v210, v211
	v_cvt_pk_bf16_f32 v202, v212, v213
	v_cvt_pk_bf16_f32 v203, v214, v215
	global_store_dwordx4 v197, v[200:203], s[20:21] sc0 sc1
	v_add_u32_e32 v197, 0x8000, v197
	s_waitcnt lgkmcnt(0)
	v_cvt_pk_bf16_f32 v204, v216, v217
	v_cvt_pk_bf16_f32 v205, v218, v219
	v_cvt_pk_bf16_f32 v206, v220, v221
	v_cvt_pk_bf16_f32 v207, v222, v223
	global_store_dwordx4 v197, v[204:207], s[20:21] sc0 sc1
	v_add_u32_e32 v197, 0x8000, v197
	ds_read2_b32 v[208:209], v192 offset0:48 offset1:113
	ds_read2_b32 v[210:211], v192 offset0:178 offset1:243
	ds_read2_b32 v[212:213], v193 offset0:52 offset1:117
	ds_read2_b32 v[214:215], v193 offset0:182 offset1:247
	ds_read2_b32 v[216:217], v192 offset0:56 offset1:121
	ds_read2_b32 v[218:219], v192 offset0:186 offset1:251
	ds_read2_b32 v[220:221], v193 offset0:60 offset1:125
	ds_read2_b32 v[222:223], v193 offset0:190 offset1:255
	s_waitcnt lgkmcnt(4)
	v_cvt_pk_bf16_f32 v200, v208, v209
	v_cvt_pk_bf16_f32 v201, v210, v211
	v_cvt_pk_bf16_f32 v202, v212, v213
	v_cvt_pk_bf16_f32 v203, v214, v215
	global_store_dwordx4 v197, v[200:203], s[20:21] sc0 sc1
	v_add_u32_e32 v197, 0x8000, v197
	s_waitcnt lgkmcnt(0)
	v_cvt_pk_bf16_f32 v204, v216, v217
	v_cvt_pk_bf16_f32 v205, v218, v219
	v_cvt_pk_bf16_f32 v206, v220, v221
	v_cvt_pk_bf16_f32 v207, v222, v223
	global_store_dwordx4 v197, v[204:207], s[20:21] sc0 sc1
	v_add_u32_e32 v197, 0x8000, v197
	s_waitcnt lgkmcnt(0)
	s_waitcnt vmcnt(23)
	v_mul_f32_e32 v64, v64, v160
	v_mul_f32_e32 v65, v65, v160
	v_mul_f32_e32 v66, v66, v160
	v_mul_f32_e32 v67, v67, v160
	ds_write2_b32 v176, v64, v65 offset1:1
	ds_write2_b32 v176, v66, v67 offset0:2 offset1:3
	s_waitcnt vmcnt(22)
	v_mul_f32_e32 v68, v68, v161
	v_mul_f32_e32 v69, v69, v161
	v_mul_f32_e32 v70, v70, v161
	v_mul_f32_e32 v71, v71, v161
	ds_write2_b32 v177, v68, v69 offset1:1
	ds_write2_b32 v177, v70, v71 offset0:2 offset1:3
	s_waitcnt vmcnt(21)
	v_mul_f32_e32 v72, v72, v162
	v_mul_f32_e32 v73, v73, v162
	v_mul_f32_e32 v74, v74, v162
	v_mul_f32_e32 v75, v75, v162
	ds_write2_b32 v178, v72, v73 offset1:1
	ds_write2_b32 v178, v74, v75 offset0:2 offset1:3
	s_waitcnt vmcnt(20)
	v_mul_f32_e32 v76, v76, v163
	v_mul_f32_e32 v77, v77, v163
	v_mul_f32_e32 v78, v78, v163
	v_mul_f32_e32 v79, v79, v163
	ds_write2_b32 v179, v76, v77 offset1:1
	ds_write2_b32 v179, v78, v79 offset0:2 offset1:3
	s_waitcnt vmcnt(19)
	v_mul_f32_e32 v80, v80, v164
	v_mul_f32_e32 v81, v81, v164
	v_mul_f32_e32 v82, v82, v164
	v_mul_f32_e32 v83, v83, v164
	ds_write2_b32 v180, v80, v81 offset1:1
	ds_write2_b32 v180, v82, v83 offset0:2 offset1:3
	s_waitcnt vmcnt(18)
	v_mul_f32_e32 v84, v84, v165
	v_mul_f32_e32 v85, v85, v165
	v_mul_f32_e32 v86, v86, v165
	v_mul_f32_e32 v87, v87, v165
	ds_write2_b32 v181, v84, v85 offset1:1
	ds_write2_b32 v181, v86, v87 offset0:2 offset1:3
	s_waitcnt vmcnt(17)
	v_mul_f32_e32 v88, v88, v166
	v_mul_f32_e32 v89, v89, v166
	v_mul_f32_e32 v90, v90, v166
	v_mul_f32_e32 v91, v91, v166
	ds_write2_b32 v182, v88, v89 offset1:1
	ds_write2_b32 v182, v90, v91 offset0:2 offset1:3
	s_waitcnt vmcnt(16)
	v_mul_f32_e32 v92, v92, v167
	v_mul_f32_e32 v93, v93, v167
	v_mul_f32_e32 v94, v94, v167
	v_mul_f32_e32 v95, v95, v167
	ds_write2_b32 v183, v92, v93 offset1:1
	ds_write2_b32 v183, v94, v95 offset0:2 offset1:3
	s_waitcnt vmcnt(15)
	v_mul_f32_e32 v96, v96, v168
	v_mul_f32_e32 v97, v97, v168
	v_mul_f32_e32 v98, v98, v168
	v_mul_f32_e32 v99, v99, v168
	ds_write2_b32 v184, v96, v97 offset1:1
	ds_write2_b32 v184, v98, v99 offset0:2 offset1:3
	s_waitcnt vmcnt(14)
	v_mul_f32_e32 v100, v100, v169
	v_mul_f32_e32 v101, v101, v169
	v_mul_f32_e32 v102, v102, v169
	v_mul_f32_e32 v103, v103, v169
	ds_write2_b32 v185, v100, v101 offset1:1
	ds_write2_b32 v185, v102, v103 offset0:2 offset1:3
	s_waitcnt vmcnt(13)
	v_mul_f32_e32 v104, v104, v170
	v_mul_f32_e32 v105, v105, v170
	v_mul_f32_e32 v106, v106, v170
	v_mul_f32_e32 v107, v107, v170
	ds_write2_b32 v186, v104, v105 offset1:1
	ds_write2_b32 v186, v106, v107 offset0:2 offset1:3
	s_waitcnt vmcnt(12)
	v_mul_f32_e32 v108, v108, v171
	v_mul_f32_e32 v109, v109, v171
	v_mul_f32_e32 v110, v110, v171
	v_mul_f32_e32 v111, v111, v171
	ds_write2_b32 v187, v108, v109 offset1:1
	ds_write2_b32 v187, v110, v111 offset0:2 offset1:3
	s_waitcnt vmcnt(11)
	v_mul_f32_e32 v112, v112, v172
	v_mul_f32_e32 v113, v113, v172
	v_mul_f32_e32 v114, v114, v172
	v_mul_f32_e32 v115, v115, v172
	ds_write2_b32 v188, v112, v113 offset1:1
	ds_write2_b32 v188, v114, v115 offset0:2 offset1:3
	s_waitcnt vmcnt(10)
	v_mul_f32_e32 v116, v116, v173
	v_mul_f32_e32 v117, v117, v173
	v_mul_f32_e32 v118, v118, v173
	v_mul_f32_e32 v119, v119, v173
	ds_write2_b32 v189, v116, v117 offset1:1
	ds_write2_b32 v189, v118, v119 offset0:2 offset1:3
	s_waitcnt vmcnt(9)
	v_mul_f32_e32 v120, v120, v174
	v_mul_f32_e32 v121, v121, v174
	v_mul_f32_e32 v122, v122, v174
	v_mul_f32_e32 v123, v123, v174
	ds_write2_b32 v190, v120, v121 offset1:1
	ds_write2_b32 v190, v122, v123 offset0:2 offset1:3
	s_waitcnt vmcnt(8)
	v_mul_f32_e32 v124, v124, v175
	v_mul_f32_e32 v125, v125, v175
	v_mul_f32_e32 v126, v126, v175
	v_mul_f32_e32 v127, v127, v175
	ds_write2_b32 v191, v124, v125 offset1:1
	ds_write2_b32 v191, v126, v127 offset0:2 offset1:3
	s_waitcnt lgkmcnt(0)
	v_mov_b32_e32 v197, v196
	ds_read2_b32 v[208:209], v192 offset0:0 offset1:65
	ds_read2_b32 v[210:211], v192 offset0:130 offset1:195
	ds_read2_b32 v[212:213], v193 offset0:4 offset1:69
	ds_read2_b32 v[214:215], v193 offset0:134 offset1:199
	ds_read2_b32 v[216:217], v192 offset0:8 offset1:73
	ds_read2_b32 v[218:219], v192 offset0:138 offset1:203
	ds_read2_b32 v[220:221], v193 offset0:12 offset1:77
	ds_read2_b32 v[222:223], v193 offset0:142 offset1:207
	s_waitcnt lgkmcnt(4)
	v_cvt_pk_bf16_f32 v200, v208, v209
	v_cvt_pk_bf16_f32 v201, v210, v211
	v_cvt_pk_bf16_f32 v202, v212, v213
	v_cvt_pk_bf16_f32 v203, v214, v215
	global_store_dwordx4 v197, v[200:203], s[26:27] sc0 sc1
	v_add_u32_e32 v197, 0x8000, v197
	s_waitcnt lgkmcnt(0)
	v_cvt_pk_bf16_f32 v204, v216, v217
	v_cvt_pk_bf16_f32 v205, v218, v219
	v_cvt_pk_bf16_f32 v206, v220, v221
	v_cvt_pk_bf16_f32 v207, v222, v223
	global_store_dwordx4 v197, v[204:207], s[26:27] sc0 sc1
	v_add_u32_e32 v197, 0x8000, v197
	ds_read2_b32 v[208:209], v192 offset0:16 offset1:81
	ds_read2_b32 v[210:211], v192 offset0:146 offset1:211
	ds_read2_b32 v[212:213], v193 offset0:20 offset1:85
	ds_read2_b32 v[214:215], v193 offset0:150 offset1:215
	ds_read2_b32 v[216:217], v192 offset0:24 offset1:89
	ds_read2_b32 v[218:219], v192 offset0:154 offset1:219
	ds_read2_b32 v[220:221], v193 offset0:28 offset1:93
	ds_read2_b32 v[222:223], v193 offset0:158 offset1:223
	s_waitcnt lgkmcnt(4)
	v_cvt_pk_bf16_f32 v200, v208, v209
	v_cvt_pk_bf16_f32 v201, v210, v211
	v_cvt_pk_bf16_f32 v202, v212, v213
	v_cvt_pk_bf16_f32 v203, v214, v215
	global_store_dwordx4 v197, v[200:203], s[26:27] sc0 sc1
	v_add_u32_e32 v197, 0x8000, v197
	s_waitcnt lgkmcnt(0)
	v_cvt_pk_bf16_f32 v204, v216, v217
	v_cvt_pk_bf16_f32 v205, v218, v219
	v_cvt_pk_bf16_f32 v206, v220, v221
	v_cvt_pk_bf16_f32 v207, v222, v223
	global_store_dwordx4 v197, v[204:207], s[26:27] sc0 sc1
	v_add_u32_e32 v197, 0x8000, v197
	ds_read2_b32 v[208:209], v192 offset0:32 offset1:97
	ds_read2_b32 v[210:211], v192 offset0:162 offset1:227
	ds_read2_b32 v[212:213], v193 offset0:36 offset1:101
	ds_read2_b32 v[214:215], v193 offset0:166 offset1:231
	ds_read2_b32 v[216:217], v192 offset0:40 offset1:105
	ds_read2_b32 v[218:219], v192 offset0:170 offset1:235
	ds_read2_b32 v[220:221], v193 offset0:44 offset1:109
	ds_read2_b32 v[222:223], v193 offset0:174 offset1:239
	s_waitcnt lgkmcnt(4)
	v_cvt_pk_bf16_f32 v200, v208, v209
	v_cvt_pk_bf16_f32 v201, v210, v211
	v_cvt_pk_bf16_f32 v202, v212, v213
	v_cvt_pk_bf16_f32 v203, v214, v215
	global_store_dwordx4 v197, v[200:203], s[26:27] sc0 sc1
	v_add_u32_e32 v197, 0x8000, v197
	s_waitcnt lgkmcnt(0)
	v_cvt_pk_bf16_f32 v204, v216, v217
	v_cvt_pk_bf16_f32 v205, v218, v219
	v_cvt_pk_bf16_f32 v206, v220, v221
	v_cvt_pk_bf16_f32 v207, v222, v223
	global_store_dwordx4 v197, v[204:207], s[26:27] sc0 sc1
	v_add_u32_e32 v197, 0x8000, v197
	ds_read2_b32 v[208:209], v192 offset0:48 offset1:113
	ds_read2_b32 v[210:211], v192 offset0:178 offset1:243
	ds_read2_b32 v[212:213], v193 offset0:52 offset1:117
	ds_read2_b32 v[214:215], v193 offset0:182 offset1:247
	ds_read2_b32 v[216:217], v192 offset0:56 offset1:121
	ds_read2_b32 v[218:219], v192 offset0:186 offset1:251
	ds_read2_b32 v[220:221], v193 offset0:60 offset1:125
	ds_read2_b32 v[222:223], v193 offset0:190 offset1:255
	s_waitcnt lgkmcnt(4)
	v_cvt_pk_bf16_f32 v200, v208, v209
	v_cvt_pk_bf16_f32 v201, v210, v211
	v_cvt_pk_bf16_f32 v202, v212, v213
	v_cvt_pk_bf16_f32 v203, v214, v215
	global_store_dwordx4 v197, v[200:203], s[26:27] sc0 sc1
	v_add_u32_e32 v197, 0x8000, v197
	s_waitcnt lgkmcnt(0)
	v_cvt_pk_bf16_f32 v204, v216, v217
	v_cvt_pk_bf16_f32 v205, v218, v219
	v_cvt_pk_bf16_f32 v206, v220, v221
	v_cvt_pk_bf16_f32 v207, v222, v223
	global_store_dwordx4 v197, v[204:207], s[26:27] sc0 sc1
	v_add_u32_e32 v197, 0x8000, v197

.LBB0_1082:
	v_lshl_add_u32 v164, s47, 8, v148
	v_and_b32_e32 v155, 12, v150
	v_add_u32_e32 v155, v150, v155
	v_lshl_or_b32 v144, s22, 8, v155
	v_ashrrev_i32_e32 v165, 31, v164
	v_ashrrev_i32_e32 v145, 31, v144
	v_lshlrev_b64 v[156:157], 11, v[164:165]
	v_lshl_add_u64 v[156:157], v[156:157], 0, v[144:145]
	v_lshl_add_u64 v[160:161], v[156:157], 2, s[48:49]
	v_lshl_add_u64 v[162:163], v[156:157], 1, s[8:9]
	global_load_dwordx4 v[168:171], v[160:161], off
	global_load_dwordx4 v[172:175], v[160:161], off offset:16
	global_load_dwordx4 v[176:179], v[160:161], off offset:512
	global_load_dwordx4 v[180:183], v[160:161], off offset:528
	v_mov_b64_e32 v[216:217], v[160:161]
	v_mov_b64_e32 v[218:219], v[162:163]
	v_xor_b32_e32 v194, 16, v154
	v_lshlrev_b32_e32 v194, 2, v194
	v_xor_b32_e32 v195, 32, v154
	v_lshlrev_b32_e32 v195, 2, v195
	s_mov_b32 s90, 0x10000
	s_mov_b32 s91, 0
	s_mov_b32 s92, 0x80000
	s_mov_b32 s93, 0
	s_mov_b32 s94, 0x20000
	s_mov_b32 s95, 0
	s_mov_b32 s96, 0x100000
	s_mov_b32 s97, 0
	v_lshl_add_u64 v[160:161], v[160:161], 0, s[94:95]
	global_load_dwordx4 v[200:203], v[160:161], off
	global_load_dwordx4 v[204:207], v[160:161], off offset:16
	global_load_dwordx4 v[208:211], v[160:161], off offset:512
	global_load_dwordx4 v[212:215], v[160:161], off offset:528
	s_waitcnt vmcnt(4)
	v_pk_add_f32 v[124:125], v[124:125], v[168:169]
	v_pk_add_f32 v[126:127], v[126:127], v[170:171]
	v_cvt_pk_bf16_f32 v184, v124, v125
	v_cvt_pk_bf16_f32 v185, v126, v127
	v_mul_f32_e32 v192, v124, v124
	v_fmac_f32_e32 v192, v125, v125
	v_fmac_f32_e32 v192, v126, v126
	v_fmac_f32_e32 v192, v127, v127
	v_pk_add_f32 v[120:121], v[120:121], v[172:173]
	v_pk_add_f32 v[122:123], v[122:123], v[174:175]
	v_cvt_pk_bf16_f32 v186, v120, v121
	v_cvt_pk_bf16_f32 v187, v122, v123
	v_fmac_f32_e32 v192, v120, v120
	v_fmac_f32_e32 v192, v121, v121
	v_fmac_f32_e32 v192, v122, v122
	v_fmac_f32_e32 v192, v123, v123
	global_store_dwordx4 v[162:163], v[184:187], off sc0 sc1
	v_pk_add_f32 v[116:117], v[116:117], v[176:177]
	v_pk_add_f32 v[118:119], v[118:119], v[178:179]
	v_cvt_pk_bf16_f32 v188, v116, v117
	v_cvt_pk_bf16_f32 v189, v118, v119
	v_fmac_f32_e32 v192, v116, v116
	v_fmac_f32_e32 v192, v117, v117
	v_fmac_f32_e32 v192, v118, v118
	v_fmac_f32_e32 v192, v119, v119
	v_pk_add_f32 v[112:113], v[112:113], v[180:181]
	v_pk_add_f32 v[114:115], v[114:115], v[182:183]
	v_cvt_pk_bf16_f32 v190, v112, v113
	v_cvt_pk_bf16_f32 v191, v114, v115
	v_fmac_f32_e32 v192, v112, v112
	v_fmac_f32_e32 v192, v113, v113
	v_fmac_f32_e32 v192, v114, v114
	v_fmac_f32_e32 v192, v115, v115
	global_store_dwordx4 v[162:163], v[188:191], off offset:256 sc0 sc1
	ds_bpermute_b32 v193, v194, v192
	s_waitcnt lgkmcnt(0)
	v_add_f32_e32 v192, v192, v193
	ds_bpermute_b32 v193, v195, v192
	v_lshl_add_u64 v[196:197], v[164:165], 2, s[10:11]
	s_waitcnt lgkmcnt(0)
	v_add_f32_e32 v192, v192, v193
	s_and_saveexec_b64 s[22:23], s[0:1]
	global_atomic_add_f32 v[196:197], v192, off
	s_or_b64 exec, exec, s[22:23]
	v_lshl_add_u64 v[162:163], v[162:163], 0, s[90:91]
	v_add_u32_e32 v164, 16, v164
	v_lshl_add_u64 v[160:161], v[160:161], 0, s[94:95]
	global_load_dwordx4 v[168:171], v[160:161], off
	global_load_dwordx4 v[172:175], v[160:161], off offset:16
	global_load_dwordx4 v[176:179], v[160:161], off offset:512
	global_load_dwordx4 v[180:183], v[160:161], off offset:528
	s_waitcnt vmcnt(6)
	v_pk_add_f32 v[108:109], v[108:109], v[200:201]
	v_pk_add_f32 v[110:111], v[110:111], v[202:203]
	v_cvt_pk_bf16_f32 v184, v108, v109
	v_cvt_pk_bf16_f32 v185, v110, v111
	v_mul_f32_e32 v192, v108, v108
	v_fmac_f32_e32 v192, v109, v109
	v_fmac_f32_e32 v192, v110, v110
	v_fmac_f32_e32 v192, v111, v111
	v_pk_add_f32 v[104:105], v[104:105], v[204:205]
	v_pk_add_f32 v[106:107], v[106:107], v[206:207]
	v_cvt_pk_bf16_f32 v186, v104, v105
	v_cvt_pk_bf16_f32 v187, v106, v107
	v_fmac_f32_e32 v192, v104, v104
	v_fmac_f32_e32 v192, v105, v105
	v_fmac_f32_e32 v192, v106, v106
	v_fmac_f32_e32 v192, v107, v107
	global_store_dwordx4 v[162:163], v[184:187], off sc0 sc1
	v_pk_add_f32 v[100:101], v[100:101], v[208:209]
	v_pk_add_f32 v[102:103], v[102:103], v[210:211]
	v_cvt_pk_bf16_f32 v188, v100, v101
	v_cvt_pk_bf16_f32 v189, v102, v103
	v_fmac_f32_e32 v192, v100, v100
	v_fmac_f32_e32 v192, v101, v101
	v_fmac_f32_e32 v192, v102, v102
	v_fmac_f32_e32 v192, v103, v103
	v_pk_add_f32 v[96:97], v[96:97], v[212:213]
	v_pk_add_f32 v[98:99], v[98:99], v[214:215]
	v_cvt_pk_bf16_f32 v190, v96, v97
	v_cvt_pk_bf16_f32 v191, v98, v99
	v_fmac_f32_e32 v192, v96, v96
	v_fmac_f32_e32 v192, v97, v97
	v_fmac_f32_e32 v192, v98, v98
	v_fmac_f32_e32 v192, v99, v99
	global_store_dwordx4 v[162:163], v[188:191], off offset:256 sc0 sc1
	ds_bpermute_b32 v193, v194, v192
	s_waitcnt lgkmcnt(0)
	v_add_f32_e32 v192, v192, v193
	ds_bpermute_b32 v193, v195, v192
	v_lshl_add_u64 v[196:197], v[164:165], 2, s[10:11]
	s_waitcnt lgkmcnt(0)
	v_add_f32_e32 v192, v192, v193
	s_and_saveexec_b64 s[22:23], s[0:1]
	global_atomic_add_f32 v[196:197], v192, off
	s_or_b64 exec, exec, s[22:23]
	v_lshl_add_u64 v[162:163], v[162:163], 0, s[90:91]
	v_add_u32_e32 v164, 16, v164
	v_lshl_add_u64 v[160:161], v[160:161], 0, s[94:95]
	global_load_dwordx4 v[200:203], v[160:161], off
	global_load_dwordx4 v[204:207], v[160:161], off offset:16
	global_load_dwordx4 v[208:211], v[160:161], off offset:512
	global_load_dwordx4 v[212:215], v[160:161], off offset:528
	s_waitcnt vmcnt(6)
	v_pk_add_f32 v[92:93], v[92:93], v[168:169]
	v_pk_add_f32 v[94:95], v[94:95], v[170:171]
	v_cvt_pk_bf16_f32 v184, v92, v93
	v_cvt_pk_bf16_f32 v185, v94, v95
	v_mul_f32_e32 v192, v92, v92
	v_fmac_f32_e32 v192, v93, v93
	v_fmac_f32_e32 v192, v94, v94
	v_fmac_f32_e32 v192, v95, v95
	v_pk_add_f32 v[88:89], v[88:89], v[172:173]
	v_pk_add_f32 v[90:91], v[90:91], v[174:175]
	v_cvt_pk_bf16_f32 v186, v88, v89
	v_cvt_pk_bf16_f32 v187, v90, v91
	v_fmac_f32_e32 v192, v88, v88
	v_fmac_f32_e32 v192, v89, v89
	v_fmac_f32_e32 v192, v90, v90
	v_fmac_f32_e32 v192, v91, v91
	global_store_dwordx4 v[162:163], v[184:187], off sc0 sc1
	v_pk_add_f32 v[84:85], v[84:85], v[176:177]
	v_pk_add_f32 v[86:87], v[86:87], v[178:179]
	v_cvt_pk_bf16_f32 v188, v84, v85
	v_cvt_pk_bf16_f32 v189, v86, v87
	v_fmac_f32_e32 v192, v84, v84
	v_fmac_f32_e32 v192, v85, v85
	v_fmac_f32_e32 v192, v86, v86
	v_fmac_f32_e32 v192, v87, v87
	v_pk_add_f32 v[80:81], v[80:81], v[180:181]
	v_pk_add_f32 v[82:83], v[82:83], v[182:183]
	v_cvt_pk_bf16_f32 v190, v80, v81
	v_cvt_pk_bf16_f32 v191, v82, v83
	v_fmac_f32_e32 v192, v80, v80
	v_fmac_f32_e32 v192, v81, v81
	v_fmac_f32_e32 v192, v82, v82
	v_fmac_f32_e32 v192, v83, v83
	global_store_dwordx4 v[162:163], v[188:191], off offset:256 sc0 sc1
	ds_bpermute_b32 v193, v194, v192
	s_waitcnt lgkmcnt(0)
	v_add_f32_e32 v192, v192, v193
	ds_bpermute_b32 v193, v195, v192
	v_lshl_add_u64 v[196:197], v[164:165], 2, s[10:11]
	s_waitcnt lgkmcnt(0)
	v_add_f32_e32 v192, v192, v193
	s_and_saveexec_b64 s[22:23], s[0:1]
	global_atomic_add_f32 v[196:197], v192, off
	s_or_b64 exec, exec, s[22:23]
	v_lshl_add_u64 v[162:163], v[162:163], 0, s[90:91]
	v_add_u32_e32 v164, 16, v164
	v_lshl_add_u64 v[160:161], v[216:217], 0, s[96:97]
	global_load_dwordx4 v[168:171], v[160:161], off
	global_load_dwordx4 v[172:175], v[160:161], off offset:16
	global_load_dwordx4 v[176:179], v[160:161], off offset:512
	global_load_dwordx4 v[180:183], v[160:161], off offset:528
	s_waitcnt vmcnt(6)
	v_pk_add_f32 v[76:77], v[76:77], v[200:201]
	v_pk_add_f32 v[78:79], v[78:79], v[202:203]
	v_cvt_pk_bf16_f32 v184, v76, v77
	v_cvt_pk_bf16_f32 v185, v78, v79
	v_mul_f32_e32 v192, v76, v76
	v_fmac_f32_e32 v192, v77, v77
	v_fmac_f32_e32 v192, v78, v78
	v_fmac_f32_e32 v192, v79, v79
	v_pk_add_f32 v[72:73], v[72:73], v[204:205]
	v_pk_add_f32 v[74:75], v[74:75], v[206:207]
	v_cvt_pk_bf16_f32 v186, v72, v73
	v_cvt_pk_bf16_f32 v187, v74, v75
	v_fmac_f32_e32 v192, v72, v72
	v_fmac_f32_e32 v192, v73, v73
	v_fmac_f32_e32 v192, v74, v74
	v_fmac_f32_e32 v192, v75, v75
	global_store_dwordx4 v[162:163], v[184:187], off sc0 sc1
	v_pk_add_f32 v[68:69], v[68:69], v[208:209]
	v_pk_add_f32 v[70:71], v[70:71], v[210:211]
	v_cvt_pk_bf16_f32 v188, v68, v69
	v_cvt_pk_bf16_f32 v189, v70, v71
	v_fmac_f32_e32 v192, v68, v68
	v_fmac_f32_e32 v192, v69, v69
	v_fmac_f32_e32 v192, v70, v70
	v_fmac_f32_e32 v192, v71, v71
	v_pk_add_f32 v[64:65], v[64:65], v[212:213]
	v_pk_add_f32 v[66:67], v[66:67], v[214:215]
	v_cvt_pk_bf16_f32 v190, v64, v65
	v_cvt_pk_bf16_f32 v191, v66, v67
	v_fmac_f32_e32 v192, v64, v64
	v_fmac_f32_e32 v192, v65, v65
	v_fmac_f32_e32 v192, v66, v66
	v_fmac_f32_e32 v192, v67, v67
	global_store_dwordx4 v[162:163], v[188:191], off offset:256 sc0 sc1
	ds_bpermute_b32 v193, v194, v192
	s_waitcnt lgkmcnt(0)
	v_add_f32_e32 v192, v192, v193
	ds_bpermute_b32 v193, v195, v192
	v_lshl_add_u64 v[196:197], v[164:165], 2, s[10:11]
	s_waitcnt lgkmcnt(0)
	v_add_f32_e32 v192, v192, v193
	s_and_saveexec_b64 s[22:23], s[0:1]
	global_atomic_add_f32 v[196:197], v192, off
	s_or_b64 exec, exec, s[22:23]
	v_lshl_add_u64 v[162:163], v[218:219], 0, s[92:93]
	v_add_u32_e32 v164, 0x50, v164
	v_lshl_add_u64 v[160:161], v[160:161], 0, s[94:95]
	global_load_dwordx4 v[200:203], v[160:161], off
	global_load_dwordx4 v[204:207], v[160:161], off offset:16
	global_load_dwordx4 v[208:211], v[160:161], off offset:512
	global_load_dwordx4 v[212:215], v[160:161], off offset:528
	s_waitcnt vmcnt(6)
	v_pk_add_f32 v[60:61], v[60:61], v[168:169]
	v_pk_add_f32 v[62:63], v[62:63], v[170:171]
	v_cvt_pk_bf16_f32 v184, v60, v61
	v_cvt_pk_bf16_f32 v185, v62, v63
	v_mul_f32_e32 v192, v60, v60
	v_fmac_f32_e32 v192, v61, v61
	v_fmac_f32_e32 v192, v62, v62
	v_fmac_f32_e32 v192, v63, v63
	v_pk_add_f32 v[56:57], v[56:57], v[172:173]
	v_pk_add_f32 v[58:59], v[58:59], v[174:175]
	v_cvt_pk_bf16_f32 v186, v56, v57
	v_cvt_pk_bf16_f32 v187, v58, v59
	v_fmac_f32_e32 v192, v56, v56
	v_fmac_f32_e32 v192, v57, v57
	v_fmac_f32_e32 v192, v58, v58
	v_fmac_f32_e32 v192, v59, v59
	global_store_dwordx4 v[162:163], v[184:187], off sc0 sc1
	v_pk_add_f32 v[52:53], v[52:53], v[176:177]
	v_pk_add_f32 v[54:55], v[54:55], v[178:179]
	v_cvt_pk_bf16_f32 v188, v52, v53
	v_cvt_pk_bf16_f32 v189, v54, v55
	v_fmac_f32_e32 v192, v52, v52
	v_fmac_f32_e32 v192, v53, v53
	v_fmac_f32_e32 v192, v54, v54
	v_fmac_f32_e32 v192, v55, v55
	v_pk_add_f32 v[48:49], v[48:49], v[180:181]
	v_pk_add_f32 v[50:51], v[50:51], v[182:183]
	v_cvt_pk_bf16_f32 v190, v48, v49
	v_cvt_pk_bf16_f32 v191, v50, v51
	v_fmac_f32_e32 v192, v48, v48
	v_fmac_f32_e32 v192, v49, v49
	v_fmac_f32_e32 v192, v50, v50
	v_fmac_f32_e32 v192, v51, v51
	global_store_dwordx4 v[162:163], v[188:191], off offset:256 sc0 sc1
	ds_bpermute_b32 v193, v194, v192
	s_waitcnt lgkmcnt(0)
	v_add_f32_e32 v192, v192, v193
	ds_bpermute_b32 v193, v195, v192
	v_lshl_add_u64 v[196:197], v[164:165], 2, s[10:11]
	s_waitcnt lgkmcnt(0)
	v_add_f32_e32 v192, v192, v193
	s_and_saveexec_b64 s[22:23], s[0:1]
	global_atomic_add_f32 v[196:197], v192, off
	s_or_b64 exec, exec, s[22:23]
	v_lshl_add_u64 v[162:163], v[162:163], 0, s[90:91]
	v_add_u32_e32 v164, 16, v164
	v_lshl_add_u64 v[160:161], v[160:161], 0, s[94:95]
	global_load_dwordx4 v[168:171], v[160:161], off
	global_load_dwordx4 v[172:175], v[160:161], off offset:16
	global_load_dwordx4 v[176:179], v[160:161], off offset:512
	global_load_dwordx4 v[180:183], v[160:161], off offset:528
	s_waitcnt vmcnt(6)
	v_pk_add_f32 v[44:45], v[44:45], v[200:201]
	v_pk_add_f32 v[46:47], v[46:47], v[202:203]
	v_cvt_pk_bf16_f32 v184, v44, v45
	v_cvt_pk_bf16_f32 v185, v46, v47
	v_mul_f32_e32 v192, v44, v44
	v_fmac_f32_e32 v192, v45, v45
	v_fmac_f32_e32 v192, v46, v46
	v_fmac_f32_e32 v192, v47, v47
	v_pk_add_f32 v[40:41], v[40:41], v[204:205]
	v_pk_add_f32 v[42:43], v[42:43], v[206:207]
	v_cvt_pk_bf16_f32 v186, v40, v41
	v_cvt_pk_bf16_f32 v187, v42, v43
	v_fmac_f32_e32 v192, v40, v40
	v_fmac_f32_e32 v192, v41, v41
	v_fmac_f32_e32 v192, v42, v42
	v_fmac_f32_e32 v192, v43, v43
	global_store_dwordx4 v[162:163], v[184:187], off sc0 sc1
	v_pk_add_f32 v[36:37], v[36:37], v[208:209]
	v_pk_add_f32 v[38:39], v[38:39], v[210:211]
	v_cvt_pk_bf16_f32 v188, v36, v37
	v_cvt_pk_bf16_f32 v189, v38, v39
	v_fmac_f32_e32 v192, v36, v36
	v_fmac_f32_e32 v192, v37, v37
	v_fmac_f32_e32 v192, v38, v38
	v_fmac_f32_e32 v192, v39, v39
	v_pk_add_f32 v[32:33], v[32:33], v[212:213]
	v_pk_add_f32 v[34:35], v[34:35], v[214:215]
	v_cvt_pk_bf16_f32 v190, v32, v33
	v_cvt_pk_bf16_f32 v191, v34, v35
	v_fmac_f32_e32 v192, v32, v32
	v_fmac_f32_e32 v192, v33, v33
	v_fmac_f32_e32 v192, v34, v34
	v_fmac_f32_e32 v192, v35, v35
	global_store_dwordx4 v[162:163], v[188:191], off offset:256 sc0 sc1
	ds_bpermute_b32 v193, v194, v192
	s_waitcnt lgkmcnt(0)
	v_add_f32_e32 v192, v192, v193
	ds_bpermute_b32 v193, v195, v192
	v_lshl_add_u64 v[196:197], v[164:165], 2, s[10:11]
	s_waitcnt lgkmcnt(0)
	v_add_f32_e32 v192, v192, v193
	s_and_saveexec_b64 s[22:23], s[0:1]
	global_atomic_add_f32 v[196:197], v192, off
	s_or_b64 exec, exec, s[22:23]
	v_lshl_add_u64 v[162:163], v[162:163], 0, s[90:91]
	v_add_u32_e32 v164, 16, v164
	v_lshl_add_u64 v[160:161], v[160:161], 0, s[94:95]
	global_load_dwordx4 v[200:203], v[160:161], off
	global_load_dwordx4 v[204:207], v[160:161], off offset:16
	global_load_dwordx4 v[208:211], v[160:161], off offset:512
	global_load_dwordx4 v[212:215], v[160:161], off offset:528
	s_waitcnt vmcnt(6)
	v_pk_add_f32 v[28:29], v[28:29], v[168:169]
	v_pk_add_f32 v[30:31], v[30:31], v[170:171]
	v_cvt_pk_bf16_f32 v184, v28, v29
	v_cvt_pk_bf16_f32 v185, v30, v31
	v_mul_f32_e32 v192, v28, v28
	v_fmac_f32_e32 v192, v29, v29
	v_fmac_f32_e32 v192, v30, v30
	v_fmac_f32_e32 v192, v31, v31
	v_pk_add_f32 v[24:25], v[24:25], v[172:173]
	v_pk_add_f32 v[26:27], v[26:27], v[174:175]
	v_cvt_pk_bf16_f32 v186, v24, v25
	v_cvt_pk_bf16_f32 v187, v26, v27
	v_fmac_f32_e32 v192, v24, v24
	v_fmac_f32_e32 v192, v25, v25
	v_fmac_f32_e32 v192, v26, v26
	v_fmac_f32_e32 v192, v27, v27
	global_store_dwordx4 v[162:163], v[184:187], off sc0 sc1
	v_pk_add_f32 v[20:21], v[20:21], v[176:177]
	v_pk_add_f32 v[22:23], v[22:23], v[178:179]
	v_cvt_pk_bf16_f32 v188, v20, v21
	v_cvt_pk_bf16_f32 v189, v22, v23
	v_fmac_f32_e32 v192, v20, v20
	v_fmac_f32_e32 v192, v21, v21
	v_fmac_f32_e32 v192, v22, v22
	v_fmac_f32_e32 v192, v23, v23
	v_pk_add_f32 v[16:17], v[16:17], v[180:181]
	v_pk_add_f32 v[18:19], v[18:19], v[182:183]
	v_cvt_pk_bf16_f32 v190, v16, v17
	v_cvt_pk_bf16_f32 v191, v18, v19
	v_fmac_f32_e32 v192, v16, v16
	v_fmac_f32_e32 v192, v17, v17
	v_fmac_f32_e32 v192, v18, v18
	v_fmac_f32_e32 v192, v19, v19
	global_store_dwordx4 v[162:163], v[188:191], off offset:256 sc0 sc1
	ds_bpermute_b32 v193, v194, v192
	s_waitcnt lgkmcnt(0)
	v_add_f32_e32 v192, v192, v193
	ds_bpermute_b32 v193, v195, v192
	v_lshl_add_u64 v[196:197], v[164:165], 2, s[10:11]
	s_waitcnt lgkmcnt(0)
	v_add_f32_e32 v192, v192, v193
	s_and_saveexec_b64 s[22:23], s[0:1]
	global_atomic_add_f32 v[196:197], v192, off
	s_or_b64 exec, exec, s[22:23]
	v_lshl_add_u64 v[162:163], v[162:163], 0, s[90:91]
	v_add_u32_e32 v164, 16, v164
	s_waitcnt vmcnt(2)
	v_pk_add_f32 v[12:13], v[12:13], v[200:201]
	v_pk_add_f32 v[14:15], v[14:15], v[202:203]
	v_cvt_pk_bf16_f32 v184, v12, v13
	v_cvt_pk_bf16_f32 v185, v14, v15
	v_mul_f32_e32 v192, v12, v12
	v_fmac_f32_e32 v192, v13, v13
	v_fmac_f32_e32 v192, v14, v14
	v_fmac_f32_e32 v192, v15, v15
	v_pk_add_f32 v[8:9], v[8:9], v[204:205]
	v_pk_add_f32 v[10:11], v[10:11], v[206:207]
	v_cvt_pk_bf16_f32 v186, v8, v9
	v_cvt_pk_bf16_f32 v187, v10, v11
	v_fmac_f32_e32 v192, v8, v8
	v_fmac_f32_e32 v192, v9, v9
	v_fmac_f32_e32 v192, v10, v10
	v_fmac_f32_e32 v192, v11, v11
	global_store_dwordx4 v[162:163], v[184:187], off sc0 sc1
	v_pk_add_f32 v[4:5], v[4:5], v[208:209]
	v_pk_add_f32 v[6:7], v[6:7], v[210:211]
	v_cvt_pk_bf16_f32 v188, v4, v5
	v_cvt_pk_bf16_f32 v189, v6, v7
	v_fmac_f32_e32 v192, v4, v4
	v_fmac_f32_e32 v192, v5, v5
	v_fmac_f32_e32 v192, v6, v6
	v_fmac_f32_e32 v192, v7, v7
	v_pk_add_f32 v[0:1], v[0:1], v[212:213]
	v_pk_add_f32 v[2:3], v[2:3], v[214:215]
	v_cvt_pk_bf16_f32 v190, v0, v1
	v_cvt_pk_bf16_f32 v191, v2, v3
	v_fmac_f32_e32 v192, v0, v0
	v_fmac_f32_e32 v192, v1, v1
	v_fmac_f32_e32 v192, v2, v2
	v_fmac_f32_e32 v192, v3, v3
	global_store_dwordx4 v[162:163], v[188:191], off offset:256 sc0 sc1
	ds_bpermute_b32 v193, v194, v192
	s_waitcnt lgkmcnt(0)
	v_add_f32_e32 v192, v192, v193
	ds_bpermute_b32 v193, v195, v192
	v_lshl_add_u64 v[196:197], v[164:165], 2, s[10:11]
	s_waitcnt lgkmcnt(0)
	v_add_f32_e32 v192, v192, v193
	s_and_saveexec_b64 s[22:23], s[0:1]
	global_atomic_add_f32 v[196:197], v192, off
	s_or_b64 exec, exec, s[22:23]
	s_andn2_b64 vcc, exec, s[2:3]
	s_mov_b64 s[2:3], -1
	s_cbranch_vccnz .LBB0_1069
	s_andn2_b64 vcc, exec, s[6:7]
	s_cbranch_vccnz .LBB0_1068
	s_barrier
	s_branch .LBB0_1068

.LBB0_1334:
	v_lshl_add_u32 v164, s26, 8, v144
	v_and_b32_e32 v151, 12, v146
	v_add_u32_e32 v151, v146, v151
	v_lshl_or_b32 v140, s28, 8, v151
	v_ashrrev_i32_e32 v165, 31, v164
	v_ashrrev_i32_e32 v141, 31, v140
	v_lshlrev_b64 v[152:153], 11, v[164:165]
	v_lshl_add_u64 v[152:153], v[152:153], 0, v[140:141]
	v_lshlrev_b64 v[152:153], 1, v[152:153]
	v_lshl_add_u64 v[160:161], s[6:7], 0, v[152:153]
	v_lshl_add_u64 v[162:163], s[8:9], 0, v[152:153]
	global_load_dwordx4 v[168:171], v[160:161], off
	global_load_dwordx4 v[172:175], v[160:161], off offset:256
	v_mov_b64_e32 v[154:155], v[160:161]
	v_mov_b64_e32 v[156:157], v[162:163]
	v_xor_b32_e32 v194, 16, v150
	v_lshlrev_b32_e32 v194, 2, v194
	v_xor_b32_e32 v195, 32, v150
	v_lshlrev_b32_e32 v195, 2, v195
	s_mov_b32 s90, 0x10000
	s_mov_b32 s91, 0
	s_mov_b32 s92, 0x80000
	s_mov_b32 s93, 0
	v_lshl_add_u64 v[160:161], v[160:161], 0, s[90:91]
	global_load_dwordx4 v[200:203], v[160:161], off
	global_load_dwordx4 v[204:207], v[160:161], off offset:256
	s_waitcnt vmcnt(2)
	v_lshlrev_b32_e32 v176, 16, v168
	v_and_b32_e32 v177, 0xffff0000, v168
	v_lshlrev_b32_e32 v178, 16, v169
	v_and_b32_e32 v179, 0xffff0000, v169
	v_pk_add_f32 v[124:125], v[124:125], v[176:177]
	v_pk_add_f32 v[126:127], v[126:127], v[178:179]
	v_cvt_pk_bf16_f32 v184, v124, v125
	v_cvt_pk_bf16_f32 v185, v126, v127
	v_mul_f32_e32 v192, v124, v124
	v_fmac_f32_e32 v192, v125, v125
	v_fmac_f32_e32 v192, v126, v126
	v_fmac_f32_e32 v192, v127, v127
	v_lshlrev_b32_e32 v176, 16, v170
	v_and_b32_e32 v177, 0xffff0000, v170
	v_lshlrev_b32_e32 v178, 16, v171
	v_and_b32_e32 v179, 0xffff0000, v171
	v_pk_add_f32 v[120:121], v[120:121], v[176:177]
	v_pk_add_f32 v[122:123], v[122:123], v[178:179]
	v_cvt_pk_bf16_f32 v186, v120, v121
	v_cvt_pk_bf16_f32 v187, v122, v123
	v_fmac_f32_e32 v192, v120, v120
	v_fmac_f32_e32 v192, v121, v121
	v_fmac_f32_e32 v192, v122, v122
	v_fmac_f32_e32 v192, v123, v123
	global_store_dwordx4 v[162:163], v[184:187], off sc0 sc1
	v_lshlrev_b32_e32 v176, 16, v172
	v_and_b32_e32 v177, 0xffff0000, v172
	v_lshlrev_b32_e32 v178, 16, v173
	v_and_b32_e32 v179, 0xffff0000, v173
	v_pk_add_f32 v[116:117], v[116:117], v[176:177]
	v_pk_add_f32 v[118:119], v[118:119], v[178:179]
	v_cvt_pk_bf16_f32 v188, v116, v117
	v_cvt_pk_bf16_f32 v189, v118, v119
	v_fmac_f32_e32 v192, v116, v116
	v_fmac_f32_e32 v192, v117, v117
	v_fmac_f32_e32 v192, v118, v118
	v_fmac_f32_e32 v192, v119, v119
	v_lshlrev_b32_e32 v176, 16, v174
	v_and_b32_e32 v177, 0xffff0000, v174
	v_lshlrev_b32_e32 v178, 16, v175
	v_and_b32_e32 v179, 0xffff0000, v175
	v_pk_add_f32 v[112:113], v[112:113], v[176:177]
	v_pk_add_f32 v[114:115], v[114:115], v[178:179]
	v_cvt_pk_bf16_f32 v190, v112, v113
	v_cvt_pk_bf16_f32 v191, v114, v115
	v_fmac_f32_e32 v192, v112, v112
	v_fmac_f32_e32 v192, v113, v113
	v_fmac_f32_e32 v192, v114, v114
	v_fmac_f32_e32 v192, v115, v115
	global_store_dwordx4 v[162:163], v[188:191], off offset:256 sc0 sc1
	ds_bpermute_b32 v193, v194, v192
	s_waitcnt lgkmcnt(0)
	v_add_f32_e32 v192, v192, v193
	ds_bpermute_b32 v193, v195, v192
	v_lshl_add_u64 v[196:197], v[164:165], 2, s[10:11]
	s_waitcnt lgkmcnt(0)
	v_add_f32_e32 v192, v192, v193
	s_and_saveexec_b64 s[26:27], s[0:1]
	global_atomic_add_f32 v[196:197], v192, off
	s_or_b64 exec, exec, s[26:27]
	v_lshl_add_u64 v[162:163], v[162:163], 0, s[90:91]
	v_add_u32_e32 v164, 16, v164
	v_lshl_add_u64 v[160:161], v[160:161], 0, s[90:91]
	global_load_dwordx4 v[168:171], v[160:161], off
	global_load_dwordx4 v[172:175], v[160:161], off offset:256
	s_waitcnt vmcnt(4)
	v_lshlrev_b32_e32 v176, 16, v200
	v_and_b32_e32 v177, 0xffff0000, v200
	v_lshlrev_b32_e32 v178, 16, v201
	v_and_b32_e32 v179, 0xffff0000, v201
	v_pk_add_f32 v[108:109], v[108:109], v[176:177]
	v_pk_add_f32 v[110:111], v[110:111], v[178:179]
	v_cvt_pk_bf16_f32 v184, v108, v109
	v_cvt_pk_bf16_f32 v185, v110, v111
	v_mul_f32_e32 v192, v108, v108
	v_fmac_f32_e32 v192, v109, v109
	v_fmac_f32_e32 v192, v110, v110
	v_fmac_f32_e32 v192, v111, v111
	v_lshlrev_b32_e32 v176, 16, v202
	v_and_b32_e32 v177, 0xffff0000, v202
	v_lshlrev_b32_e32 v178, 16, v203
	v_and_b32_e32 v179, 0xffff0000, v203
	v_pk_add_f32 v[104:105], v[104:105], v[176:177]
	v_pk_add_f32 v[106:107], v[106:107], v[178:179]
	v_cvt_pk_bf16_f32 v186, v104, v105
	v_cvt_pk_bf16_f32 v187, v106, v107
	v_fmac_f32_e32 v192, v104, v104
	v_fmac_f32_e32 v192, v105, v105
	v_fmac_f32_e32 v192, v106, v106
	v_fmac_f32_e32 v192, v107, v107
	global_store_dwordx4 v[162:163], v[184:187], off sc0 sc1
	v_lshlrev_b32_e32 v176, 16, v204
	v_and_b32_e32 v177, 0xffff0000, v204
	v_lshlrev_b32_e32 v178, 16, v205
	v_and_b32_e32 v179, 0xffff0000, v205
	v_pk_add_f32 v[100:101], v[100:101], v[176:177]
	v_pk_add_f32 v[102:103], v[102:103], v[178:179]
	v_cvt_pk_bf16_f32 v188, v100, v101
	v_cvt_pk_bf16_f32 v189, v102, v103
	v_fmac_f32_e32 v192, v100, v100
	v_fmac_f32_e32 v192, v101, v101
	v_fmac_f32_e32 v192, v102, v102
	v_fmac_f32_e32 v192, v103, v103
	v_lshlrev_b32_e32 v176, 16, v206
	v_and_b32_e32 v177, 0xffff0000, v206
	v_lshlrev_b32_e32 v178, 16, v207
	v_and_b32_e32 v179, 0xffff0000, v207
	v_pk_add_f32 v[96:97], v[96:97], v[176:177]
	v_pk_add_f32 v[98:99], v[98:99], v[178:179]
	v_cvt_pk_bf16_f32 v190, v96, v97
	v_cvt_pk_bf16_f32 v191, v98, v99
	v_fmac_f32_e32 v192, v96, v96
	v_fmac_f32_e32 v192, v97, v97
	v_fmac_f32_e32 v192, v98, v98
	v_fmac_f32_e32 v192, v99, v99
	global_store_dwordx4 v[162:163], v[188:191], off offset:256 sc0 sc1
	ds_bpermute_b32 v193, v194, v192
	s_waitcnt lgkmcnt(0)
	v_add_f32_e32 v192, v192, v193
	ds_bpermute_b32 v193, v195, v192
	v_lshl_add_u64 v[196:197], v[164:165], 2, s[10:11]
	s_waitcnt lgkmcnt(0)
	v_add_f32_e32 v192, v192, v193
	s_and_saveexec_b64 s[26:27], s[0:1]
	global_atomic_add_f32 v[196:197], v192, off
	s_or_b64 exec, exec, s[26:27]
	v_lshl_add_u64 v[162:163], v[162:163], 0, s[90:91]
	v_add_u32_e32 v164, 16, v164
	v_lshl_add_u64 v[160:161], v[160:161], 0, s[90:91]
	global_load_dwordx4 v[200:203], v[160:161], off
	global_load_dwordx4 v[204:207], v[160:161], off offset:256
	s_waitcnt vmcnt(4)
	v_lshlrev_b32_e32 v176, 16, v168
	v_and_b32_e32 v177, 0xffff0000, v168
	v_lshlrev_b32_e32 v178, 16, v169
	v_and_b32_e32 v179, 0xffff0000, v169
	v_pk_add_f32 v[92:93], v[92:93], v[176:177]
	v_pk_add_f32 v[94:95], v[94:95], v[178:179]
	v_cvt_pk_bf16_f32 v184, v92, v93
	v_cvt_pk_bf16_f32 v185, v94, v95
	v_mul_f32_e32 v192, v92, v92
	v_fmac_f32_e32 v192, v93, v93
	v_fmac_f32_e32 v192, v94, v94
	v_fmac_f32_e32 v192, v95, v95
	v_lshlrev_b32_e32 v176, 16, v170
	v_and_b32_e32 v177, 0xffff0000, v170
	v_lshlrev_b32_e32 v178, 16, v171
	v_and_b32_e32 v179, 0xffff0000, v171
	v_pk_add_f32 v[88:89], v[88:89], v[176:177]
	v_pk_add_f32 v[90:91], v[90:91], v[178:179]
	v_cvt_pk_bf16_f32 v186, v88, v89
	v_cvt_pk_bf16_f32 v187, v90, v91
	v_fmac_f32_e32 v192, v88, v88
	v_fmac_f32_e32 v192, v89, v89
	v_fmac_f32_e32 v192, v90, v90
	v_fmac_f32_e32 v192, v91, v91
	global_store_dwordx4 v[162:163], v[184:187], off sc0 sc1
	v_lshlrev_b32_e32 v176, 16, v172
	v_and_b32_e32 v177, 0xffff0000, v172
	v_lshlrev_b32_e32 v178, 16, v173
	v_and_b32_e32 v179, 0xffff0000, v173
	v_pk_add_f32 v[84:85], v[84:85], v[176:177]
	v_pk_add_f32 v[86:87], v[86:87], v[178:179]
	v_cvt_pk_bf16_f32 v188, v84, v85
	v_cvt_pk_bf16_f32 v189, v86, v87
	v_fmac_f32_e32 v192, v84, v84
	v_fmac_f32_e32 v192, v85, v85
	v_fmac_f32_e32 v192, v86, v86
	v_fmac_f32_e32 v192, v87, v87
	v_lshlrev_b32_e32 v176, 16, v174
	v_and_b32_e32 v177, 0xffff0000, v174
	v_lshlrev_b32_e32 v178, 16, v175
	v_and_b32_e32 v179, 0xffff0000, v175
	v_pk_add_f32 v[80:81], v[80:81], v[176:177]
	v_pk_add_f32 v[82:83], v[82:83], v[178:179]
	v_cvt_pk_bf16_f32 v190, v80, v81
	v_cvt_pk_bf16_f32 v191, v82, v83
	v_fmac_f32_e32 v192, v80, v80
	v_fmac_f32_e32 v192, v81, v81
	v_fmac_f32_e32 v192, v82, v82
	v_fmac_f32_e32 v192, v83, v83
	global_store_dwordx4 v[162:163], v[188:191], off offset:256 sc0 sc1
	ds_bpermute_b32 v193, v194, v192
	s_waitcnt lgkmcnt(0)
	v_add_f32_e32 v192, v192, v193
	ds_bpermute_b32 v193, v195, v192
	v_lshl_add_u64 v[196:197], v[164:165], 2, s[10:11]
	s_waitcnt lgkmcnt(0)
	v_add_f32_e32 v192, v192, v193
	s_and_saveexec_b64 s[26:27], s[0:1]
	global_atomic_add_f32 v[196:197], v192, off
	s_or_b64 exec, exec, s[26:27]
	v_lshl_add_u64 v[162:163], v[162:163], 0, s[90:91]
	v_add_u32_e32 v164, 16, v164
	v_lshl_add_u64 v[160:161], v[154:155], 0, s[92:93]
	global_load_dwordx4 v[168:171], v[160:161], off
	global_load_dwordx4 v[172:175], v[160:161], off offset:256
	s_waitcnt vmcnt(4)
	v_lshlrev_b32_e32 v176, 16, v200
	v_and_b32_e32 v177, 0xffff0000, v200
	v_lshlrev_b32_e32 v178, 16, v201
	v_and_b32_e32 v179, 0xffff0000, v201
	v_pk_add_f32 v[76:77], v[76:77], v[176:177]
	v_pk_add_f32 v[78:79], v[78:79], v[178:179]
	v_cvt_pk_bf16_f32 v184, v76, v77
	v_cvt_pk_bf16_f32 v185, v78, v79
	v_mul_f32_e32 v192, v76, v76
	v_fmac_f32_e32 v192, v77, v77
	v_fmac_f32_e32 v192, v78, v78
	v_fmac_f32_e32 v192, v79, v79
	v_lshlrev_b32_e32 v176, 16, v202
	v_and_b32_e32 v177, 0xffff0000, v202
	v_lshlrev_b32_e32 v178, 16, v203
	v_and_b32_e32 v179, 0xffff0000, v203
	v_pk_add_f32 v[72:73], v[72:73], v[176:177]
	v_pk_add_f32 v[74:75], v[74:75], v[178:179]
	v_cvt_pk_bf16_f32 v186, v72, v73
	v_cvt_pk_bf16_f32 v187, v74, v75
	v_fmac_f32_e32 v192, v72, v72
	v_fmac_f32_e32 v192, v73, v73
	v_fmac_f32_e32 v192, v74, v74
	v_fmac_f32_e32 v192, v75, v75
	global_store_dwordx4 v[162:163], v[184:187], off sc0 sc1
	v_lshlrev_b32_e32 v176, 16, v204
	v_and_b32_e32 v177, 0xffff0000, v204
	v_lshlrev_b32_e32 v178, 16, v205
	v_and_b32_e32 v179, 0xffff0000, v205
	v_pk_add_f32 v[68:69], v[68:69], v[176:177]
	v_pk_add_f32 v[70:71], v[70:71], v[178:179]
	v_cvt_pk_bf16_f32 v188, v68, v69
	v_cvt_pk_bf16_f32 v189, v70, v71
	v_fmac_f32_e32 v192, v68, v68
	v_fmac_f32_e32 v192, v69, v69
	v_fmac_f32_e32 v192, v70, v70
	v_fmac_f32_e32 v192, v71, v71
	v_lshlrev_b32_e32 v176, 16, v206
	v_and_b32_e32 v177, 0xffff0000, v206
	v_lshlrev_b32_e32 v178, 16, v207
	v_and_b32_e32 v179, 0xffff0000, v207
	v_pk_add_f32 v[64:65], v[64:65], v[176:177]
	v_pk_add_f32 v[66:67], v[66:67], v[178:179]
	v_cvt_pk_bf16_f32 v190, v64, v65
	v_cvt_pk_bf16_f32 v191, v66, v67
	v_fmac_f32_e32 v192, v64, v64
	v_fmac_f32_e32 v192, v65, v65
	v_fmac_f32_e32 v192, v66, v66
	v_fmac_f32_e32 v192, v67, v67
	global_store_dwordx4 v[162:163], v[188:191], off offset:256 sc0 sc1
	ds_bpermute_b32 v193, v194, v192
	s_waitcnt lgkmcnt(0)
	v_add_f32_e32 v192, v192, v193
	ds_bpermute_b32 v193, v195, v192
	v_lshl_add_u64 v[196:197], v[164:165], 2, s[10:11]
	s_waitcnt lgkmcnt(0)
	v_add_f32_e32 v192, v192, v193
	s_and_saveexec_b64 s[26:27], s[0:1]
	global_atomic_add_f32 v[196:197], v192, off
	s_or_b64 exec, exec, s[26:27]
	v_lshl_add_u64 v[162:163], v[156:157], 0, s[92:93]
	v_add_u32_e32 v164, 0x50, v164
	v_lshl_add_u64 v[160:161], v[160:161], 0, s[90:91]
	global_load_dwordx4 v[200:203], v[160:161], off
	global_load_dwordx4 v[204:207], v[160:161], off offset:256
	s_waitcnt vmcnt(4)
	v_lshlrev_b32_e32 v176, 16, v168
	v_and_b32_e32 v177, 0xffff0000, v168
	v_lshlrev_b32_e32 v178, 16, v169
	v_and_b32_e32 v179, 0xffff0000, v169
	v_pk_add_f32 v[60:61], v[60:61], v[176:177]
	v_pk_add_f32 v[62:63], v[62:63], v[178:179]
	v_cvt_pk_bf16_f32 v184, v60, v61
	v_cvt_pk_bf16_f32 v185, v62, v63
	v_mul_f32_e32 v192, v60, v60
	v_fmac_f32_e32 v192, v61, v61
	v_fmac_f32_e32 v192, v62, v62
	v_fmac_f32_e32 v192, v63, v63
	v_lshlrev_b32_e32 v176, 16, v170
	v_and_b32_e32 v177, 0xffff0000, v170
	v_lshlrev_b32_e32 v178, 16, v171
	v_and_b32_e32 v179, 0xffff0000, v171
	v_pk_add_f32 v[56:57], v[56:57], v[176:177]
	v_pk_add_f32 v[58:59], v[58:59], v[178:179]
	v_cvt_pk_bf16_f32 v186, v56, v57
	v_cvt_pk_bf16_f32 v187, v58, v59
	v_fmac_f32_e32 v192, v56, v56
	v_fmac_f32_e32 v192, v57, v57
	v_fmac_f32_e32 v192, v58, v58
	v_fmac_f32_e32 v192, v59, v59
	global_store_dwordx4 v[162:163], v[184:187], off sc0 sc1
	v_lshlrev_b32_e32 v176, 16, v172
	v_and_b32_e32 v177, 0xffff0000, v172
	v_lshlrev_b32_e32 v178, 16, v173
	v_and_b32_e32 v179, 0xffff0000, v173
	v_pk_add_f32 v[52:53], v[52:53], v[176:177]
	v_pk_add_f32 v[54:55], v[54:55], v[178:179]
	v_cvt_pk_bf16_f32 v188, v52, v53
	v_cvt_pk_bf16_f32 v189, v54, v55
	v_fmac_f32_e32 v192, v52, v52
	v_fmac_f32_e32 v192, v53, v53
	v_fmac_f32_e32 v192, v54, v54
	v_fmac_f32_e32 v192, v55, v55
	v_lshlrev_b32_e32 v176, 16, v174
	v_and_b32_e32 v177, 0xffff0000, v174
	v_lshlrev_b32_e32 v178, 16, v175
	v_and_b32_e32 v179, 0xffff0000, v175
	v_pk_add_f32 v[48:49], v[48:49], v[176:177]
	v_pk_add_f32 v[50:51], v[50:51], v[178:179]
	v_cvt_pk_bf16_f32 v190, v48, v49
	v_cvt_pk_bf16_f32 v191, v50, v51
	v_fmac_f32_e32 v192, v48, v48
	v_fmac_f32_e32 v192, v49, v49
	v_fmac_f32_e32 v192, v50, v50
	v_fmac_f32_e32 v192, v51, v51
	global_store_dwordx4 v[162:163], v[188:191], off offset:256 sc0 sc1
	ds_bpermute_b32 v193, v194, v192
	s_waitcnt lgkmcnt(0)
	v_add_f32_e32 v192, v192, v193
	ds_bpermute_b32 v193, v195, v192
	v_lshl_add_u64 v[196:197], v[164:165], 2, s[10:11]
	s_waitcnt lgkmcnt(0)
	v_add_f32_e32 v192, v192, v193
	s_and_saveexec_b64 s[26:27], s[0:1]
	global_atomic_add_f32 v[196:197], v192, off
	s_or_b64 exec, exec, s[26:27]
	v_lshl_add_u64 v[162:163], v[162:163], 0, s[90:91]
	v_add_u32_e32 v164, 16, v164
	v_lshl_add_u64 v[160:161], v[160:161], 0, s[90:91]
	global_load_dwordx4 v[168:171], v[160:161], off
	global_load_dwordx4 v[172:175], v[160:161], off offset:256
	s_waitcnt vmcnt(4)
	v_lshlrev_b32_e32 v176, 16, v200
	v_and_b32_e32 v177, 0xffff0000, v200
	v_lshlrev_b32_e32 v178, 16, v201
	v_and_b32_e32 v179, 0xffff0000, v201
	v_pk_add_f32 v[44:45], v[44:45], v[176:177]
	v_pk_add_f32 v[46:47], v[46:47], v[178:179]
	v_cvt_pk_bf16_f32 v184, v44, v45
	v_cvt_pk_bf16_f32 v185, v46, v47
	v_mul_f32_e32 v192, v44, v44
	v_fmac_f32_e32 v192, v45, v45
	v_fmac_f32_e32 v192, v46, v46
	v_fmac_f32_e32 v192, v47, v47
	v_lshlrev_b32_e32 v176, 16, v202
	v_and_b32_e32 v177, 0xffff0000, v202
	v_lshlrev_b32_e32 v178, 16, v203
	v_and_b32_e32 v179, 0xffff0000, v203
	v_pk_add_f32 v[40:41], v[40:41], v[176:177]
	v_pk_add_f32 v[42:43], v[42:43], v[178:179]
	v_cvt_pk_bf16_f32 v186, v40, v41
	v_cvt_pk_bf16_f32 v187, v42, v43
	v_fmac_f32_e32 v192, v40, v40
	v_fmac_f32_e32 v192, v41, v41
	v_fmac_f32_e32 v192, v42, v42
	v_fmac_f32_e32 v192, v43, v43
	global_store_dwordx4 v[162:163], v[184:187], off sc0 sc1
	v_lshlrev_b32_e32 v176, 16, v204
	v_and_b32_e32 v177, 0xffff0000, v204
	v_lshlrev_b32_e32 v178, 16, v205
	v_and_b32_e32 v179, 0xffff0000, v205
	v_pk_add_f32 v[36:37], v[36:37], v[176:177]
	v_pk_add_f32 v[38:39], v[38:39], v[178:179]
	v_cvt_pk_bf16_f32 v188, v36, v37
	v_cvt_pk_bf16_f32 v189, v38, v39
	v_fmac_f32_e32 v192, v36, v36
	v_fmac_f32_e32 v192, v37, v37
	v_fmac_f32_e32 v192, v38, v38
	v_fmac_f32_e32 v192, v39, v39
	v_lshlrev_b32_e32 v176, 16, v206
	v_and_b32_e32 v177, 0xffff0000, v206
	v_lshlrev_b32_e32 v178, 16, v207
	v_and_b32_e32 v179, 0xffff0000, v207
	v_pk_add_f32 v[32:33], v[32:33], v[176:177]
	v_pk_add_f32 v[34:35], v[34:35], v[178:179]
	v_cvt_pk_bf16_f32 v190, v32, v33
	v_cvt_pk_bf16_f32 v191, v34, v35
	v_fmac_f32_e32 v192, v32, v32
	v_fmac_f32_e32 v192, v33, v33
	v_fmac_f32_e32 v192, v34, v34
	v_fmac_f32_e32 v192, v35, v35
	global_store_dwordx4 v[162:163], v[188:191], off offset:256 sc0 sc1
	ds_bpermute_b32 v193, v194, v192
	s_waitcnt lgkmcnt(0)
	v_add_f32_e32 v192, v192, v193
	ds_bpermute_b32 v193, v195, v192
	v_lshl_add_u64 v[196:197], v[164:165], 2, s[10:11]
	s_waitcnt lgkmcnt(0)
	v_add_f32_e32 v192, v192, v193
	s_and_saveexec_b64 s[26:27], s[0:1]
	global_atomic_add_f32 v[196:197], v192, off
	s_or_b64 exec, exec, s[26:27]
	v_lshl_add_u64 v[162:163], v[162:163], 0, s[90:91]
	v_add_u32_e32 v164, 16, v164
	v_lshl_add_u64 v[160:161], v[160:161], 0, s[90:91]
	global_load_dwordx4 v[200:203], v[160:161], off
	global_load_dwordx4 v[204:207], v[160:161], off offset:256
	s_waitcnt vmcnt(4)
	v_lshlrev_b32_e32 v176, 16, v168
	v_and_b32_e32 v177, 0xffff0000, v168
	v_lshlrev_b32_e32 v178, 16, v169
	v_and_b32_e32 v179, 0xffff0000, v169
	v_pk_add_f32 v[28:29], v[28:29], v[176:177]
	v_pk_add_f32 v[30:31], v[30:31], v[178:179]
	v_cvt_pk_bf16_f32 v184, v28, v29
	v_cvt_pk_bf16_f32 v185, v30, v31
	v_mul_f32_e32 v192, v28, v28
	v_fmac_f32_e32 v192, v29, v29
	v_fmac_f32_e32 v192, v30, v30
	v_fmac_f32_e32 v192, v31, v31
	v_lshlrev_b32_e32 v176, 16, v170
	v_and_b32_e32 v177, 0xffff0000, v170
	v_lshlrev_b32_e32 v178, 16, v171
	v_and_b32_e32 v179, 0xffff0000, v171
	v_pk_add_f32 v[24:25], v[24:25], v[176:177]
	v_pk_add_f32 v[26:27], v[26:27], v[178:179]
	v_cvt_pk_bf16_f32 v186, v24, v25
	v_cvt_pk_bf16_f32 v187, v26, v27
	v_fmac_f32_e32 v192, v24, v24
	v_fmac_f32_e32 v192, v25, v25
	v_fmac_f32_e32 v192, v26, v26
	v_fmac_f32_e32 v192, v27, v27
	global_store_dwordx4 v[162:163], v[184:187], off sc0 sc1
	v_lshlrev_b32_e32 v176, 16, v172
	v_and_b32_e32 v177, 0xffff0000, v172
	v_lshlrev_b32_e32 v178, 16, v173
	v_and_b32_e32 v179, 0xffff0000, v173
	v_pk_add_f32 v[20:21], v[20:21], v[176:177]
	v_pk_add_f32 v[22:23], v[22:23], v[178:179]
	v_cvt_pk_bf16_f32 v188, v20, v21
	v_cvt_pk_bf16_f32 v189, v22, v23
	v_fmac_f32_e32 v192, v20, v20
	v_fmac_f32_e32 v192, v21, v21
	v_fmac_f32_e32 v192, v22, v22
	v_fmac_f32_e32 v192, v23, v23
	v_lshlrev_b32_e32 v176, 16, v174
	v_and_b32_e32 v177, 0xffff0000, v174
	v_lshlrev_b32_e32 v178, 16, v175
	v_and_b32_e32 v179, 0xffff0000, v175
	v_pk_add_f32 v[16:17], v[16:17], v[176:177]
	v_pk_add_f32 v[18:19], v[18:19], v[178:179]
	v_cvt_pk_bf16_f32 v190, v16, v17
	v_cvt_pk_bf16_f32 v191, v18, v19
	v_fmac_f32_e32 v192, v16, v16
	v_fmac_f32_e32 v192, v17, v17
	v_fmac_f32_e32 v192, v18, v18
	v_fmac_f32_e32 v192, v19, v19
	global_store_dwordx4 v[162:163], v[188:191], off offset:256 sc0 sc1
	ds_bpermute_b32 v193, v194, v192
	s_waitcnt lgkmcnt(0)
	v_add_f32_e32 v192, v192, v193
	ds_bpermute_b32 v193, v195, v192
	v_lshl_add_u64 v[196:197], v[164:165], 2, s[10:11]
	s_waitcnt lgkmcnt(0)
	v_add_f32_e32 v192, v192, v193
	s_and_saveexec_b64 s[26:27], s[0:1]
	global_atomic_add_f32 v[196:197], v192, off
	s_or_b64 exec, exec, s[26:27]
	v_lshl_add_u64 v[162:163], v[162:163], 0, s[90:91]
	v_add_u32_e32 v164, 16, v164
	s_waitcnt vmcnt(2)
	v_lshlrev_b32_e32 v176, 16, v200
	v_and_b32_e32 v177, 0xffff0000, v200
	v_lshlrev_b32_e32 v178, 16, v201
	v_and_b32_e32 v179, 0xffff0000, v201
	v_pk_add_f32 v[12:13], v[12:13], v[176:177]
	v_pk_add_f32 v[14:15], v[14:15], v[178:179]
	v_cvt_pk_bf16_f32 v184, v12, v13
	v_cvt_pk_bf16_f32 v185, v14, v15
	v_mul_f32_e32 v192, v12, v12
	v_fmac_f32_e32 v192, v13, v13
	v_fmac_f32_e32 v192, v14, v14
	v_fmac_f32_e32 v192, v15, v15
	v_lshlrev_b32_e32 v176, 16, v202
	v_and_b32_e32 v177, 0xffff0000, v202
	v_lshlrev_b32_e32 v178, 16, v203
	v_and_b32_e32 v179, 0xffff0000, v203
	v_pk_add_f32 v[8:9], v[8:9], v[176:177]
	v_pk_add_f32 v[10:11], v[10:11], v[178:179]
	v_cvt_pk_bf16_f32 v186, v8, v9
	v_cvt_pk_bf16_f32 v187, v10, v11
	v_fmac_f32_e32 v192, v8, v8
	v_fmac_f32_e32 v192, v9, v9
	v_fmac_f32_e32 v192, v10, v10
	v_fmac_f32_e32 v192, v11, v11
	global_store_dwordx4 v[162:163], v[184:187], off sc0 sc1
	v_lshlrev_b32_e32 v176, 16, v204
	v_and_b32_e32 v177, 0xffff0000, v204
	v_lshlrev_b32_e32 v178, 16, v205
	v_and_b32_e32 v179, 0xffff0000, v205
	v_pk_add_f32 v[4:5], v[4:5], v[176:177]
	v_pk_add_f32 v[6:7], v[6:7], v[178:179]
	v_cvt_pk_bf16_f32 v188, v4, v5
	v_cvt_pk_bf16_f32 v189, v6, v7
	v_fmac_f32_e32 v192, v4, v4
	v_fmac_f32_e32 v192, v5, v5
	v_fmac_f32_e32 v192, v6, v6
	v_fmac_f32_e32 v192, v7, v7
	v_lshlrev_b32_e32 v176, 16, v206
	v_and_b32_e32 v177, 0xffff0000, v206
	v_lshlrev_b32_e32 v178, 16, v207
	v_and_b32_e32 v179, 0xffff0000, v207
	v_pk_add_f32 v[0:1], v[0:1], v[176:177]
	v_pk_add_f32 v[2:3], v[2:3], v[178:179]
	v_cvt_pk_bf16_f32 v190, v0, v1
	v_cvt_pk_bf16_f32 v191, v2, v3
	v_fmac_f32_e32 v192, v0, v0
	v_fmac_f32_e32 v192, v1, v1
	v_fmac_f32_e32 v192, v2, v2
	v_fmac_f32_e32 v192, v3, v3
	global_store_dwordx4 v[162:163], v[188:191], off offset:256 sc0 sc1
	ds_bpermute_b32 v193, v194, v192
	s_waitcnt lgkmcnt(0)
	v_add_f32_e32 v192, v192, v193
	ds_bpermute_b32 v193, v195, v192
	v_lshl_add_u64 v[196:197], v[164:165], 2, s[10:11]
	s_waitcnt lgkmcnt(0)
	v_add_f32_e32 v192, v192, v193
	s_and_saveexec_b64 s[26:27], s[0:1]
	global_atomic_add_f32 v[196:197], v192, off
	s_or_b64 exec, exec, s[26:27]
	s_andn2_b64 vcc, exec, s[2:3]
	s_mov_b64 s[2:3], -1
	s_cbranch_vccnz .LBB0_1323
	s_andn2_b64 vcc, exec, s[4:5]
	s_cbranch_vccnz .LBB0_1322
	s_barrier
	s_branch .LBB0_1322
